# K-loop code placement: loop heads at a 64-byte boundary (phase 0 instead of 44), chosen with an in-kernel K-loop timer
# speedup vs baseline: 1.0081x; 1.0015x over previous
; #define PG8_STAGE(bufoff, gbase, voff) do { _Pragma("unroll") for (int _i = 0; _i < 2; ++_i) \
;         __builtin_amdgcn_global_load_lds((const unsigned*)((const char*)(gbase) + (voff)[_i]), (LAS unsigned*)(lds + (bufoff) + ldsw + _i * 8192), 16, 0, 0); } while (0)
; #define PG8_LDA(dst, b, h) do { _Pragma("unroll") for (int m = 0; m < 4; ++m) _Pragma("unroll") for (int k = 0; k < 2; ++k) dst[m][k] = *(const LAS bf16x8*)(lds + PG8_SA(b, h) + aoff + m * 2048 + k * 1024); } while (0)
; #define PG8_LDB(dst, b, h) do { _Pragma("unroll") for (int n = 0; n < 2; ++n) _Pragma("unroll") for (int k = 0; k < 2; ++k) dst[n][k] = *(const LAS bf16x8*)(lds + PG8_SB(b, h) + boff + n * 2048 + k * 1024); } while (0)
; #define PG8_WAIT_V(n) asm volatile("s_waitcnt vmcnt(" #n ")" ::: "memory")
; #define PG8_WAIT_L(n) asm volatile("s_waitcnt lgkmcnt(" #n ")" ::: "memory")
; #define PG8_BAR __builtin_amdgcn_s_barrier()
; template <class Epi, bool ALIGN_EPI = true, bool SP2 = true>
; __device__ __forceinline__ void gemm_phase(LAS unsigned char* lds, const Gemm g, const Order& S, const Epi& E) {
;     ...
;     for (;;) {
;         const bool has_next = S.next(ui + 1, nxt);
;         const char* nA = has_next ? (const char*)(nxt.z ? g.A1 : g.A0) + (size_t)nxt.pm * tstepA + (size_t)nxt.kt0 * kstep : cA; const char* nB = has_next ? (const char*)(nxt.z ? g.B1 : g.B0) + (size_t)nxt.pn * tstepB + (size_t)nxt.kt0 * kstep : cB;
;         const int nt = cur.nkt;
;         for (int t = 0; t < nt; t += 2) {
;             const bool last = (t == nt - 2);
;             const char* a1 = cA + (size_t)(t + 1) * kstep;
;             const char* a2 = last ? nA : cA + (size_t)(t + 2) * kstep; const char* b2 = last ? nB : cB + (size_t)(t + 2) * kstep;
;             const char* a3 = a2 + kstep; const char* b3 = b2 + kstep;
;             if constexpr (SP2) {
;             PG8_LDB(B0, 0, 0); PG8_LDB(B1, 0, 1); PG8_SCHED; PG8_LDA(At, 0, 0); PG8_STAGE(PG8_SA(1, 1), a1 + hstepA, voffA);
;             PG8_WAIT_V(8); PG8_WAIT_L(0); PG8_BAR; PG8_MMA(0, 0, At, B0); PG8_MMA(0, 1, At, B1); PG8_BAR; PG8_SCHED;
;     ...
;         for (int a = 0; a < 2; ++a)
; #pragma unroll
;             for (int b = 0; b < 2; ++b)
; #pragma unroll
;                 for (int m = 0; m < 4; ++m)
; #pragma unroll
;                     for (int n = 0; n < 2; ++n) acc[a][b][m][n] = (f32x4){0.f, 0.f, 0.f, 0.f};
.LBB0_160:
	s_ashr_i32 s89, s88, 31
	s_lshl_b64 s[50:51], s[88:89], 19
	s_add_u32 s52, s23, s50
	s_addc_u32 s53, s24, s51
	s_and_b64 s[50:51], s[92:93], exec
	s_cselect_b32 s91, s53, s13
	s_cselect_b32 s90, s52, s12
	s_ashr_i32 s87, s86, 31
	s_lshl_b64 s[50:51], s[86:87], 19
	s_add_u32 s52, s60, s50
	s_addc_u32 s53, s61, s51
	s_and_b64 s[50:51], s[92:93], exec
	s_cselect_b32 s93, s53, s15
	s_cselect_b32 s92, s52, s14
	s_add_u32 s12, s12, 0x40080
	s_addc_u32 s13, s13, 0
	s_add_u32 s50, s14, 0x100
	v_mov_b32_e32 v2, 0
	s_addc_u32 s51, s15, 0
	s_mov_b32 s52, -2
	v_mov_b32_e32 v3, v2
	v_mov_b32_e32 v4, v2
	v_mov_b32_e32 v5, v2
	v_mov_b32_e32 v6, v2
	v_mov_b32_e32 v7, v2
	v_mov_b32_e32 v8, v2
	v_mov_b32_e32 v9, v2
	v_mov_b32_e32 v14, v2
	v_mov_b32_e32 v15, v2
	v_mov_b32_e32 v16, v2
	v_mov_b32_e32 v17, v2
	v_mov_b32_e32 v22, v2
	v_mov_b32_e32 v23, v2
	v_mov_b32_e32 v24, v2
	v_mov_b32_e32 v25, v2
	v_mov_b32_e32 v30, v2
	v_mov_b32_e32 v31, v2
	v_mov_b32_e32 v32, v2
	v_mov_b32_e32 v33, v2
	v_mov_b32_e32 v38, v2
	v_mov_b32_e32 v39, v2
	v_mov_b32_e32 v40, v2
	v_mov_b32_e32 v41, v2
	v_mov_b32_e32 v46, v2
	v_mov_b32_e32 v47, v2
	v_mov_b32_e32 v48, v2
	v_mov_b32_e32 v49, v2
	v_mov_b32_e32 v54, v2
	v_mov_b32_e32 v55, v2
	v_mov_b32_e32 v56, v2
	v_mov_b32_e32 v57, v2
	v_mov_b32_e32 v10, v2
	v_mov_b32_e32 v11, v2
	v_mov_b32_e32 v12, v2
	v_mov_b32_e32 v13, v2
	v_mov_b32_e32 v18, v2
	v_mov_b32_e32 v19, v2
	v_mov_b32_e32 v20, v2
	v_mov_b32_e32 v21, v2
	v_mov_b32_e32 v26, v2
	v_mov_b32_e32 v27, v2
	v_mov_b32_e32 v28, v2
	v_mov_b32_e32 v29, v2
	v_mov_b32_e32 v34, v2
	v_mov_b32_e32 v35, v2
	v_mov_b32_e32 v36, v2
	v_mov_b32_e32 v37, v2
	v_mov_b32_e32 v42, v2
	v_mov_b32_e32 v43, v2
	v_mov_b32_e32 v44, v2
	v_mov_b32_e32 v45, v2
	v_mov_b32_e32 v50, v2
	v_mov_b32_e32 v51, v2
	v_mov_b32_e32 v52, v2
	v_mov_b32_e32 v53, v2
	v_mov_b32_e32 v58, v2
	v_mov_b32_e32 v59, v2
	v_mov_b32_e32 v60, v2
	v_mov_b32_e32 v61, v2
	v_mov_b32_e32 v62, v2
	v_mov_b32_e32 v63, v2
	v_mov_b32_e32 v64, v2
	v_mov_b32_e32 v65, v2
	v_mov_b32_e32 v66, v2
	v_mov_b32_e32 v67, v2
	v_mov_b32_e32 v68, v2
	v_mov_b32_e32 v69, v2
	v_mov_b32_e32 v70, v2
	v_mov_b32_e32 v71, v2
	v_mov_b32_e32 v72, v2
	v_mov_b32_e32 v73, v2
	v_mov_b32_e32 v82, v2
	v_mov_b32_e32 v83, v2
	v_mov_b32_e32 v84, v2
	v_mov_b32_e32 v85, v2
	v_mov_b32_e32 v86, v2
	v_mov_b32_e32 v87, v2
	v_mov_b32_e32 v88, v2
	v_mov_b32_e32 v89, v2
	v_mov_b32_e32 v98, v2
	v_mov_b32_e32 v99, v2
	v_mov_b32_e32 v100, v2
	v_mov_b32_e32 v101, v2
	v_mov_b32_e32 v102, v2
	v_mov_b32_e32 v103, v2
	v_mov_b32_e32 v104, v2
	v_mov_b32_e32 v105, v2
	v_mov_b32_e32 v114, v2
	v_mov_b32_e32 v115, v2
	v_mov_b32_e32 v116, v2
	v_mov_b32_e32 v117, v2
	v_mov_b32_e32 v118, v2
	v_mov_b32_e32 v119, v2
	v_mov_b32_e32 v120, v2
	v_mov_b32_e32 v121, v2
	v_mov_b32_e32 v74, v2
	v_mov_b32_e32 v75, v2
	v_mov_b32_e32 v76, v2
	v_mov_b32_e32 v77, v2
	v_mov_b32_e32 v78, v2
	v_mov_b32_e32 v79, v2
	v_mov_b32_e32 v80, v2
	v_mov_b32_e32 v81, v2
	v_mov_b32_e32 v90, v2
	v_mov_b32_e32 v91, v2
	v_mov_b32_e32 v92, v2
	v_mov_b32_e32 v93, v2
	v_mov_b32_e32 v94, v2
	v_mov_b32_e32 v95, v2
	v_mov_b32_e32 v96, v2
	v_mov_b32_e32 v97, v2
	v_mov_b32_e32 v106, v2
	v_mov_b32_e32 v107, v2
	v_mov_b32_e32 v108, v2
	v_mov_b32_e32 v109, v2
	v_mov_b32_e32 v110, v2
	v_mov_b32_e32 v111, v2
	v_mov_b32_e32 v112, v2
	v_mov_b32_e32 v113, v2
	v_mov_b32_e32 v122, v2
	v_mov_b32_e32 v123, v2
	v_mov_b32_e32 v124, v2
	v_mov_b32_e32 v125, v2
	v_mov_b32_e32 v126, v2
	v_mov_b32_e32 v127, v2
	v_mov_b32_e32 v128, v2
	v_mov_b32_e32 v129, v2
	.p2align	6
.LBB0_161:
	s_add_u32 s14, s12, 0xfffc0080
	s_addc_u32 s15, s13, -1
	s_add_i32 s53, 0, 0x10000
	s_cmp_eq_u32 s52, 12
	s_cselect_b32 vcc_hi, s91, s15
	s_cselect_b32 vcc_lo, s90, s14
	v_add_u32_e32 v0, s53, v185
	s_cselect_b32 s15, s93, s51
	s_cselect_b32 s14, s92, s50
	s_add_i32 s58, 0, 0x14000
	ds_read_b128 v[130:133], v0
	ds_read_b128 v[134:137], v0 offset:1024
	ds_read_b128 v[138:141], v0 offset:2048
	ds_read_b128 v[142:145], v0 offset:3072
	v_add_u32_e32 v0, s58, v185
	ds_read_b128 v[146:149], v0
	ds_read_b128 v[150:153], v0 offset:1024
	ds_read_b128 v[154:157], v0 offset:2048
	ds_read_b128 v[158:161], v0 offset:3072
	v_lshl_add_u64 v[202:203], s[12:13], 0, v[172:173]
	s_add_i32 m0, s25, 0xc000
	ds_read_b128 v[176:179], v189
	ds_read_b128 v[180:183], v189 offset:1024
	ds_read_b128 v[190:193], v189 offset:2048
	ds_read_b128 v[194:197], v189 offset:3072
	ds_read_b128 v[198:201], v189 offset:4096
	ds_read_b128 v[224:227], v189 offset:5120
	ds_read_b128 v[228:231], v189 offset:6144
	ds_read_b128 v[232:235], v189 offset:7168
	global_load_lds_dwordx4 v[202:203], off
	v_lshl_add_u64 v[202:203], s[12:13], 0, v[174:175]
	s_add_i32 m0, s25, 0xe000
	s_nop 0
	global_load_lds_dwordx4 v[202:203], off
	s_waitcnt vmcnt(8)
	s_waitcnt lgkmcnt(0)
	s_barrier
; #define PG8_STAGE(bufoff, gbase, voff) do { _Pragma("unroll") for (int _i = 0; _i < 2; ++_i) \
;         __builtin_amdgcn_global_load_lds((const unsigned*)((const char*)(gbase) + (voff)[_i]), (LAS unsigned*)(lds + (bufoff) + ldsw + _i * 8192), 16, 0, 0); } while (0)
; #define PG8_LDA(dst, b, h) do { _Pragma("unroll") for (int m = 0; m < 4; ++m) _Pragma("unroll") for (int k = 0; k < 2; ++k) dst[m][k] = *(const LAS bf16x8*)(lds + PG8_SA(b, h) + aoff + m * 2048 + k * 1024); } while (0)
; #define PG8_MMA(ai, bj, At, Bt) do { __builtin_amdgcn_s_setprio(1); _Pragma("unroll") for (int m = 0; m < 4; ++m) _Pragma("unroll") for (int n = 0; n < 2; ++n) _Pragma("unroll") for (int k = 0; k < 2; ++k) \
;         acc[ai][bj][m][n] = __builtin_amdgcn_mfma_f32_16x16x32_bf16(Bt[n][k], At[m][k], acc[ai][bj][m][n], 0, 0, 0); __builtin_amdgcn_s_setprio(0); } while (0)
; #define PG8_WAIT_V(n) asm volatile("s_waitcnt vmcnt(" #n ")" ::: "memory")
; #define PG8_WAIT_L(n) asm volatile("s_waitcnt lgkmcnt(" #n ")" ::: "memory")
; #define PG8_BAR __builtin_amdgcn_s_barrier()
; #define PG8_SCHED __builtin_amdgcn_sched_barrier(0)
; template <class Epi, bool ALIGN_EPI = true, bool SP2 = true>
; __device__ __forceinline__ void gemm_phase(LAS unsigned char* lds, const Gemm g, const Order& S, const Epi& E) {
;     ...
;             PG8_WAIT_V(8); PG8_WAIT_L(0); PG8_BAR; PG8_MMA(0, 0, At, B0); PG8_MMA(0, 1, At, B1); PG8_BAR; PG8_SCHED;
;             PG8_LDA(At, 0, 1); PG8_STAGE(PG8_SB(0, 0), b2, voffB); PG8_STAGE(PG8_SB(0, 1), b2 + hstepB, voffB); PG8_STAGE(PG8_SA(0, 0), a2, voffA);
;             PG8_WAIT_V(8); PG8_WAIT_L(0); PG8_BAR; PG8_MMA(1, 0, At, B0); PG8_MMA(1, 1, At, B1); PG8_BAR; PG8_SCHED;
	s_setprio 1
	s_waitcnt lgkmcnt(0)
	v_mfma_f32_16x16x32_bf16 v[126:129], v[130:133], v[176:179], v[126:129]
	v_mfma_f32_16x16x32_bf16 v[122:125], v[138:141], v[176:179], v[122:125]
	v_mfma_f32_16x16x32_bf16 v[110:113], v[130:133], v[190:193], v[110:113]
	v_mfma_f32_16x16x32_bf16 v[106:109], v[138:141], v[190:193], v[106:109]
	v_mfma_f32_16x16x32_bf16 v[94:97], v[130:133], v[198:201], v[94:97]
	v_mfma_f32_16x16x32_bf16 v[90:93], v[138:141], v[198:201], v[90:93]
	v_mfma_f32_16x16x32_bf16 v[78:81], v[130:133], v[228:231], v[78:81]
	v_mfma_f32_16x16x32_bf16 v[74:77], v[138:141], v[228:231], v[74:77]
	v_mfma_f32_16x16x32_bf16 v[126:129], v[134:137], v[180:183], v[126:129]
	v_mfma_f32_16x16x32_bf16 v[122:125], v[142:145], v[180:183], v[122:125]
	v_mfma_f32_16x16x32_bf16 v[110:113], v[134:137], v[194:197], v[110:113]
	v_mfma_f32_16x16x32_bf16 v[106:109], v[142:145], v[194:197], v[106:109]
	v_mfma_f32_16x16x32_bf16 v[94:97], v[134:137], v[224:227], v[94:97]
	v_mfma_f32_16x16x32_bf16 v[90:93], v[142:145], v[224:227], v[90:93]
	v_mfma_f32_16x16x32_bf16 v[78:81], v[134:137], v[232:235], v[78:81]
	v_mfma_f32_16x16x32_bf16 v[74:77], v[142:145], v[232:235], v[74:77]
	s_setprio 0
	s_setprio 1
	v_mfma_f32_16x16x32_bf16 v[118:121], v[146:149], v[176:179], v[118:121]
	v_mfma_f32_16x16x32_bf16 v[114:117], v[154:157], v[176:179], v[114:117]
	v_mfma_f32_16x16x32_bf16 v[102:105], v[146:149], v[190:193], v[102:105]
	v_mfma_f32_16x16x32_bf16 v[98:101], v[154:157], v[190:193], v[98:101]
	v_mfma_f32_16x16x32_bf16 v[86:89], v[146:149], v[198:201], v[86:89]
	v_mfma_f32_16x16x32_bf16 v[82:85], v[154:157], v[198:201], v[82:85]
	v_mfma_f32_16x16x32_bf16 v[70:73], v[146:149], v[228:231], v[70:73]
	v_mfma_f32_16x16x32_bf16 v[66:69], v[154:157], v[228:231], v[66:69]
	v_mfma_f32_16x16x32_bf16 v[118:121], v[150:153], v[180:183], v[118:121]
	v_mfma_f32_16x16x32_bf16 v[114:117], v[158:161], v[180:183], v[114:117]
	v_mfma_f32_16x16x32_bf16 v[102:105], v[150:153], v[194:197], v[102:105]
	v_mfma_f32_16x16x32_bf16 v[98:101], v[158:161], v[194:197], v[98:101]
	v_mfma_f32_16x16x32_bf16 v[86:89], v[150:153], v[224:227], v[86:89]
	v_mfma_f32_16x16x32_bf16 v[82:85], v[158:161], v[224:227], v[82:85]
	v_mfma_f32_16x16x32_bf16 v[70:73], v[150:153], v[232:235], v[70:73]
	v_mfma_f32_16x16x32_bf16 v[66:69], v[158:161], v[232:235], v[66:69]
	s_setprio 0
	s_barrier
	s_add_i32 s53, s53, s21
	v_lshl_add_u64 v[202:203], s[14:15], 0, v[164:165]
	s_mov_b32 m0, s53
	ds_read_b128 v[176:179], v189 offset:16384
	ds_read_b128 v[180:183], v189 offset:17408
	ds_read_b128 v[190:193], v189 offset:18432
	ds_read_b128 v[194:197], v189 offset:19456
	ds_read_b128 v[198:201], v189 offset:20480
	ds_read_b128 v[224:227], v189 offset:21504
	ds_read_b128 v[228:231], v189 offset:22528
	ds_read_b128 v[232:235], v189 offset:23552
	global_load_lds_dwordx4 v[202:203], off
	s_add_i32 m0, s53, 0x2000
	s_add_u32 s54, s14, 0x40000
	v_lshl_add_u64 v[236:237], s[14:15], 0, v[168:169]
	s_addc_u32 s55, s15, 0
	s_add_i32 s53, s58, s21
	global_load_lds_dwordx4 v[236:237], off
	v_lshl_add_u64 v[238:239], s[54:55], 0, v[164:165]
	s_mov_b32 m0, s53
	v_lshl_add_u64 v[240:241], vcc, 0, v[166:167]
	global_load_lds_dwordx4 v[238:239], off
	v_lshl_add_u64 v[238:239], s[54:55], 0, v[168:169]
	s_add_i32 m0, s53, 0x2000
	s_nop 0
	global_load_lds_dwordx4 v[238:239], off
	v_lshl_add_u64 v[238:239], vcc, 0, v[162:163]
	s_mov_b32 m0, s25
	s_nop 0
	global_load_lds_dwordx4 v[238:239], off
	s_mov_b32 m0, s34
	s_nop 0
	global_load_lds_dwordx4 v[240:241], off
	s_waitcnt vmcnt(8)
	s_waitcnt lgkmcnt(0)
	s_barrier
	s_setprio 1
	s_waitcnt lgkmcnt(0)
	v_mfma_f32_16x16x32_bf16 v[62:65], v[130:133], v[176:179], v[62:65]
	v_mfma_f32_16x16x32_bf16 v[58:61], v[138:141], v[176:179], v[58:61]
	v_mfma_f32_16x16x32_bf16 v[50:53], v[130:133], v[190:193], v[50:53]
	v_mfma_f32_16x16x32_bf16 v[42:45], v[138:141], v[190:193], v[42:45]
	v_mfma_f32_16x16x32_bf16 v[34:37], v[130:133], v[198:201], v[34:37]
	v_mfma_f32_16x16x32_bf16 v[26:29], v[138:141], v[198:201], v[26:29]
	v_mfma_f32_16x16x32_bf16 v[18:21], v[130:133], v[228:231], v[18:21]
	v_mfma_f32_16x16x32_bf16 v[10:13], v[138:141], v[228:231], v[10:13]
	v_mfma_f32_16x16x32_bf16 v[62:65], v[134:137], v[180:183], v[62:65]
	v_mfma_f32_16x16x32_bf16 v[58:61], v[142:145], v[180:183], v[58:61]
	v_mfma_f32_16x16x32_bf16 v[50:53], v[134:137], v[194:197], v[50:53]
	v_mfma_f32_16x16x32_bf16 v[42:45], v[142:145], v[194:197], v[42:45]
	v_mfma_f32_16x16x32_bf16 v[34:37], v[134:137], v[224:227], v[34:37]
	v_mfma_f32_16x16x32_bf16 v[26:29], v[142:145], v[224:227], v[26:29]
	v_mfma_f32_16x16x32_bf16 v[18:21], v[134:137], v[232:235], v[18:21]
	v_mfma_f32_16x16x32_bf16 v[10:13], v[142:145], v[232:235], v[10:13]
	s_setprio 0
	s_setprio 1
	v_mfma_f32_16x16x32_bf16 v[54:57], v[146:149], v[176:179], v[54:57]
	v_mfma_f32_16x16x32_bf16 v[46:49], v[154:157], v[176:179], v[46:49]
	v_mfma_f32_16x16x32_bf16 v[38:41], v[146:149], v[190:193], v[38:41]
	v_mfma_f32_16x16x32_bf16 v[30:33], v[154:157], v[190:193], v[30:33]
	v_mfma_f32_16x16x32_bf16 v[22:25], v[146:149], v[198:201], v[22:25]
	v_mfma_f32_16x16x32_bf16 v[14:17], v[154:157], v[198:201], v[14:17]
	v_mfma_f32_16x16x32_bf16 v[6:9], v[146:149], v[228:231], v[6:9]
	v_mfma_f32_16x16x32_bf16 v[2:5], v[154:157], v[228:231], v[2:5]
	v_mfma_f32_16x16x32_bf16 v[54:57], v[150:153], v[180:183], v[54:57]
	v_mfma_f32_16x16x32_bf16 v[46:49], v[158:161], v[180:183], v[46:49]
	v_mfma_f32_16x16x32_bf16 v[38:41], v[150:153], v[194:197], v[38:41]
	v_mfma_f32_16x16x32_bf16 v[30:33], v[158:161], v[194:197], v[30:33]
	v_mfma_f32_16x16x32_bf16 v[22:25], v[150:153], v[224:227], v[22:25]
	v_mfma_f32_16x16x32_bf16 v[14:17], v[158:161], v[224:227], v[14:17]
	v_mfma_f32_16x16x32_bf16 v[6:9], v[150:153], v[232:235], v[6:9]
	v_mfma_f32_16x16x32_bf16 v[2:5], v[158:161], v[232:235], v[2:5]
	s_setprio 0
	s_barrier
; #define PG8_STAGE(bufoff, gbase, voff) do { _Pragma("unroll") for (int _i = 0; _i < 2; ++_i) \
;         __builtin_amdgcn_global_load_lds((const unsigned*)((const char*)(gbase) + (voff)[_i]), (LAS unsigned*)(lds + (bufoff) + ldsw + _i * 8192), 16, 0, 0); } while (0)
; #define PG8_LDA(dst, b, h) do { _Pragma("unroll") for (int m = 0; m < 4; ++m) _Pragma("unroll") for (int k = 0; k < 2; ++k) dst[m][k] = *(const LAS bf16x8*)(lds + PG8_SA(b, h) + aoff + m * 2048 + k * 1024); } while (0)
; #define PG8_LDB(dst, b, h) do { _Pragma("unroll") for (int n = 0; n < 2; ++n) _Pragma("unroll") for (int k = 0; k < 2; ++k) dst[n][k] = *(const LAS bf16x8*)(lds + PG8_SB(b, h) + boff + n * 2048 + k * 1024); } while (0)
; #define PG8_MMA(ai, bj, At, Bt) do { __builtin_amdgcn_s_setprio(1); _Pragma("unroll") for (int m = 0; m < 4; ++m) _Pragma("unroll") for (int n = 0; n < 2; ++n) _Pragma("unroll") for (int k = 0; k < 2; ++k) \
;         acc[ai][bj][m][n] = __builtin_amdgcn_mfma_f32_16x16x32_bf16(Bt[n][k], At[m][k], acc[ai][bj][m][n], 0, 0, 0); __builtin_amdgcn_s_setprio(0); } while (0)
; #define PG8_WAIT_V(n) asm volatile("s_waitcnt vmcnt(" #n ")" ::: "memory")
; #define PG8_WAIT_L(n) asm volatile("s_waitcnt lgkmcnt(" #n ")" ::: "memory")
; #define PG8_BAR __builtin_amdgcn_s_barrier()
; #define PG8_SCHED __builtin_amdgcn_sched_barrier(0)
; template <class Epi, bool ALIGN_EPI = true, bool SP2 = true>
; __device__ __forceinline__ void gemm_phase(LAS unsigned char* lds, const Gemm g, const Order& S, const Epi& E) {
;     ...
;             PG8_WAIT_V(8); PG8_WAIT_L(0); PG8_BAR; PG8_MMA(1, 0, At, B0); PG8_MMA(1, 1, At, B1); PG8_BAR; PG8_SCHED;
;             PG8_LDB(B0, 1, 0); PG8_LDB(B1, 1, 1); PG8_SCHED; PG8_LDA(At, 1, 0); PG8_STAGE(PG8_SA(0, 1), a2 + hstepA, voffA);
;             PG8_WAIT_V(8); PG8_WAIT_L(0); PG8_BAR; PG8_MMA(0, 0, At, B0); PG8_MMA(0, 1, At, B1); PG8_BAR; PG8_SCHED;
	s_add_i32 s53, 0, 0x18000
	v_add_u32_e32 v0, s53, v185
	s_add_i32 s58, 0, 0x1c000
	ds_read_b128 v[130:133], v0
	ds_read_b128 v[134:137], v0 offset:1024
	ds_read_b128 v[138:141], v0 offset:2048
	ds_read_b128 v[142:145], v0 offset:3072
	v_add_u32_e32 v0, s58, v185
	ds_read_b128 v[146:149], v0
	ds_read_b128 v[150:153], v0 offset:1024
	ds_read_b128 v[154:157], v0 offset:2048
	ds_read_b128 v[158:161], v0 offset:3072
	s_add_u32 s54, vcc_lo, 0x40000
	s_addc_u32 s55, vcc_hi, 0
	s_mov_b32 m0, s35
	v_lshl_add_u64 v[242:243], s[54:55], 0, v[162:163]
	ds_read_b128 v[176:179], v189 offset:32768
	ds_read_b128 v[180:183], v189 offset:33792
	ds_read_b128 v[190:193], v189 offset:34816
	ds_read_b128 v[194:197], v189 offset:35840
	ds_read_b128 v[198:201], v189 offset:36864
	ds_read_b128 v[224:227], v189 offset:37888
	ds_read_b128 v[228:231], v189 offset:38912
	ds_read_b128 v[232:235], v189 offset:39936
	global_load_lds_dwordx4 v[242:243], off
	v_lshl_add_u64 v[242:243], s[54:55], 0, v[166:167]
	s_mov_b32 m0, s40
	s_nop 0
	global_load_lds_dwordx4 v[242:243], off
	s_waitcnt vmcnt(8)
	s_waitcnt lgkmcnt(0)
	s_barrier
	s_setprio 1
	s_waitcnt lgkmcnt(0)
	v_mfma_f32_16x16x32_bf16 v[126:129], v[130:133], v[176:179], v[126:129]
	v_mfma_f32_16x16x32_bf16 v[122:125], v[138:141], v[176:179], v[122:125]
	v_mfma_f32_16x16x32_bf16 v[110:113], v[130:133], v[190:193], v[110:113]
	v_mfma_f32_16x16x32_bf16 v[106:109], v[138:141], v[190:193], v[106:109]
	v_mfma_f32_16x16x32_bf16 v[94:97], v[130:133], v[198:201], v[94:97]
	v_mfma_f32_16x16x32_bf16 v[90:93], v[138:141], v[198:201], v[90:93]
	v_mfma_f32_16x16x32_bf16 v[78:81], v[130:133], v[228:231], v[78:81]
	v_mfma_f32_16x16x32_bf16 v[74:77], v[138:141], v[228:231], v[74:77]
	v_mfma_f32_16x16x32_bf16 v[126:129], v[134:137], v[180:183], v[126:129]
	v_mfma_f32_16x16x32_bf16 v[122:125], v[142:145], v[180:183], v[122:125]
	v_mfma_f32_16x16x32_bf16 v[110:113], v[134:137], v[194:197], v[110:113]
	v_mfma_f32_16x16x32_bf16 v[106:109], v[142:145], v[194:197], v[106:109]
	v_mfma_f32_16x16x32_bf16 v[94:97], v[134:137], v[224:227], v[94:97]
	v_mfma_f32_16x16x32_bf16 v[90:93], v[142:145], v[224:227], v[90:93]
	v_mfma_f32_16x16x32_bf16 v[78:81], v[134:137], v[232:235], v[78:81]
	v_mfma_f32_16x16x32_bf16 v[74:77], v[142:145], v[232:235], v[74:77]
	s_setprio 0
	s_setprio 1
	v_mfma_f32_16x16x32_bf16 v[118:121], v[146:149], v[176:179], v[118:121]
	v_mfma_f32_16x16x32_bf16 v[114:117], v[154:157], v[176:179], v[114:117]
	v_mfma_f32_16x16x32_bf16 v[102:105], v[146:149], v[190:193], v[102:105]
	v_mfma_f32_16x16x32_bf16 v[98:101], v[154:157], v[190:193], v[98:101]
	v_mfma_f32_16x16x32_bf16 v[86:89], v[146:149], v[198:201], v[86:89]
	v_mfma_f32_16x16x32_bf16 v[82:85], v[154:157], v[198:201], v[82:85]
	v_mfma_f32_16x16x32_bf16 v[70:73], v[146:149], v[228:231], v[70:73]
	v_mfma_f32_16x16x32_bf16 v[66:69], v[154:157], v[228:231], v[66:69]
	v_mfma_f32_16x16x32_bf16 v[118:121], v[150:153], v[180:183], v[118:121]
	v_mfma_f32_16x16x32_bf16 v[114:117], v[158:161], v[180:183], v[114:117]
	v_mfma_f32_16x16x32_bf16 v[102:105], v[150:153], v[194:197], v[102:105]
	v_mfma_f32_16x16x32_bf16 v[98:101], v[158:161], v[194:197], v[98:101]
	v_mfma_f32_16x16x32_bf16 v[86:89], v[150:153], v[224:227], v[86:89]
	v_mfma_f32_16x16x32_bf16 v[82:85], v[158:161], v[224:227], v[82:85]
	v_mfma_f32_16x16x32_bf16 v[70:73], v[150:153], v[232:235], v[70:73]
	v_mfma_f32_16x16x32_bf16 v[66:69], v[158:161], v[232:235], v[66:69]
	s_setprio 0
	s_barrier
; #define PG8_STAGE(bufoff, gbase, voff) do { _Pragma("unroll") for (int _i = 0; _i < 2; ++_i) \
;         __builtin_amdgcn_global_load_lds((const unsigned*)((const char*)(gbase) + (voff)[_i]), (LAS unsigned*)(lds + (bufoff) + ldsw + _i * 8192), 16, 0, 0); } while (0)
; #define PG8_WAIT_V(n) asm volatile("s_waitcnt vmcnt(" #n ")" ::: "memory")
; #define PG8_WAIT_L(n) asm volatile("s_waitcnt lgkmcnt(" #n ")" ::: "memory")
; #define PG8_BAR __builtin_amdgcn_s_barrier()
; template <class Epi, bool ALIGN_EPI = true, bool SP2 = true>
; __device__ __forceinline__ void gemm_phase(LAS unsigned char* lds, const Gemm g, const Order& S, const Epi& E) {
;     ...
;             PG8_WAIT_V(8); PG8_WAIT_L(0); PG8_BAR; PG8_MMA(0, 0, At, B0); PG8_MMA(0, 1, At, B1); PG8_BAR; PG8_SCHED;
;             PG8_LDA(At, 1, 1); PG8_STAGE(PG8_SB(1, 0), b3, voffB); PG8_STAGE(PG8_SB(1, 1), b3 + hstepB, voffB); PG8_STAGE(PG8_SA(1, 0), a3, voffA);
;             PG8_WAIT_V(8); PG8_WAIT_L(0); PG8_BAR; PG8_MMA(1, 0, At, B0); PG8_MMA(1, 1, At, B1); PG8_BAR; PG8_SCHED;
;             } else {
;             PG8_LDB(B0, 0, 0); PG8_SCHED; PG8_LDA(At, 0, 0); PG8_STAGE(PG8_SA(1, 1), a1 + hstepA, voffA);
;             PG8_WAIT_L(8); PG8_BAR; PG8_WAIT_L(0); PG8_MMA(0, 0, At, B0); PG8_BAR; PG8_SCHED;
;             PG8_LDB(B1, 0, 1); PG8_STAGE(PG8_SB(0, 0), b2, voffB);
;             PG8_BAR; PG8_WAIT_L(0); PG8_MMA(0, 1, At, B1); PG8_BAR;
;             PG8_LDA(At, 0, 1); PG8_STAGE(PG8_SA(0, 0), a2, voffA);
;             PG8_BAR; PG8_WAIT_L(0); PG8_MMA(1, 0, At, B0); PG8_BAR; PG8_SCHED;
;             PG8_STAGE(PG8_SB(0, 1), b2 + hstepB, voffB);
;             PG8_WAIT_V(6); PG8_BAR; PG8_MMA(1, 1, At, B1); PG8_BAR;
;             PG8_LDB(B0, 1, 0); PG8_SCHED; PG8_LDA(At, 1, 0); PG8_STAGE(PG8_SA(0, 1), a2 + hstepA, voffA);
;             PG8_WAIT_L(8); PG8_BAR; PG8_WAIT_L(0); PG8_MMA(0, 0, At, B0); PG8_BAR; PG8_SCHED;
;             PG8_LDB(B1, 1, 1); PG8_STAGE(PG8_SB(1, 0), b3, voffB);
;             PG8_BAR; PG8_WAIT_L(0); PG8_MMA(0, 1, At, B1); PG8_BAR;
;             PG8_LDA(At, 1, 1); PG8_STAGE(PG8_SA(1, 0), a3, voffA);
;             PG8_BAR; PG8_WAIT_L(0); PG8_MMA(1, 0, At, B0); PG8_BAR; PG8_SCHED;
;             PG8_STAGE(PG8_SB(1, 1), b3 + hstepB, voffB);
;             PG8_WAIT_V(6); PG8_BAR; PG8_MMA(1, 1, At, B1); PG8_BAR;
;             }
;         }
;         if constexpr (ALIGN_EPI) { if (wr == 0) PG8_BAR; }
	s_add_i32 s53, s53, s21
	v_lshl_add_u64 v[202:203], v[202:203], 0, s[26:27]
	s_mov_b32 m0, s53
	ds_read_b128 v[176:179], v189 offset:49152
	ds_read_b128 v[180:183], v189 offset:50176
	ds_read_b128 v[190:193], v189 offset:51200
	ds_read_b128 v[194:197], v189 offset:52224
	ds_read_b128 v[198:201], v189 offset:53248
	ds_read_b128 v[224:227], v189 offset:54272
	ds_read_b128 v[228:231], v189 offset:55296
	ds_read_b128 v[232:235], v189 offset:56320
	global_load_lds_dwordx4 v[202:203], off
	s_add_i32 m0, s53, 0x2000
	s_add_u32 s14, s14, 0x40080
	v_lshl_add_u64 v[202:203], v[236:237], 0, s[26:27]
	s_addc_u32 s15, s15, 0
	s_add_i32 s53, s58, s21
	global_load_lds_dwordx4 v[202:203], off
	v_lshl_add_u64 v[202:203], s[14:15], 0, v[164:165]
	s_mov_b32 m0, s53
	s_nop 0
	global_load_lds_dwordx4 v[202:203], off
	v_lshl_add_u64 v[202:203], s[14:15], 0, v[168:169]
	s_add_i32 m0, s53, 0x2000
	s_nop 0
	global_load_lds_dwordx4 v[202:203], off
	v_lshl_add_u64 v[202:203], v[238:239], 0, s[26:27]
	s_mov_b32 m0, s44
	s_nop 0
	global_load_lds_dwordx4 v[202:203], off
	v_lshl_add_u64 v[202:203], v[240:241], 0, s[26:27]
	s_mov_b32 m0, s45
	s_nop 0
	global_load_lds_dwordx4 v[202:203], off
	s_waitcnt vmcnt(8)
	s_waitcnt lgkmcnt(0)
	s_barrier
	s_setprio 1
	s_waitcnt lgkmcnt(0)
	v_mfma_f32_16x16x32_bf16 v[62:65], v[130:133], v[176:179], v[62:65]
	v_mfma_f32_16x16x32_bf16 v[58:61], v[138:141], v[176:179], v[58:61]
	v_mfma_f32_16x16x32_bf16 v[50:53], v[130:133], v[190:193], v[50:53]
	v_mfma_f32_16x16x32_bf16 v[42:45], v[138:141], v[190:193], v[42:45]
	v_mfma_f32_16x16x32_bf16 v[34:37], v[130:133], v[198:201], v[34:37]
	v_mfma_f32_16x16x32_bf16 v[26:29], v[138:141], v[198:201], v[26:29]
	v_mfma_f32_16x16x32_bf16 v[18:21], v[130:133], v[228:231], v[18:21]
	v_mfma_f32_16x16x32_bf16 v[10:13], v[138:141], v[228:231], v[10:13]
	v_mfma_f32_16x16x32_bf16 v[62:65], v[134:137], v[180:183], v[62:65]
	v_mfma_f32_16x16x32_bf16 v[58:61], v[142:145], v[180:183], v[58:61]
	v_mfma_f32_16x16x32_bf16 v[50:53], v[134:137], v[194:197], v[50:53]
	v_mfma_f32_16x16x32_bf16 v[42:45], v[142:145], v[194:197], v[42:45]
	v_mfma_f32_16x16x32_bf16 v[34:37], v[134:137], v[224:227], v[34:37]
	v_mfma_f32_16x16x32_bf16 v[26:29], v[142:145], v[224:227], v[26:29]
	v_mfma_f32_16x16x32_bf16 v[18:21], v[134:137], v[232:235], v[18:21]
	v_mfma_f32_16x16x32_bf16 v[10:13], v[142:145], v[232:235], v[10:13]
	s_setprio 0
	s_setprio 1
	v_mfma_f32_16x16x32_bf16 v[54:57], v[146:149], v[176:179], v[54:57]
	v_mfma_f32_16x16x32_bf16 v[46:49], v[154:157], v[176:179], v[46:49]
	v_mfma_f32_16x16x32_bf16 v[38:41], v[146:149], v[190:193], v[38:41]
	v_mfma_f32_16x16x32_bf16 v[30:33], v[154:157], v[190:193], v[30:33]
	v_mfma_f32_16x16x32_bf16 v[22:25], v[146:149], v[198:201], v[22:25]
	v_mfma_f32_16x16x32_bf16 v[14:17], v[154:157], v[198:201], v[14:17]
	v_mfma_f32_16x16x32_bf16 v[6:9], v[146:149], v[228:231], v[6:9]
	v_mfma_f32_16x16x32_bf16 v[2:5], v[154:157], v[228:231], v[2:5]
	v_mfma_f32_16x16x32_bf16 v[54:57], v[150:153], v[180:183], v[54:57]
	v_mfma_f32_16x16x32_bf16 v[46:49], v[158:161], v[180:183], v[46:49]
	v_mfma_f32_16x16x32_bf16 v[38:41], v[150:153], v[194:197], v[38:41]
	v_mfma_f32_16x16x32_bf16 v[30:33], v[158:161], v[194:197], v[30:33]
	v_mfma_f32_16x16x32_bf16 v[22:25], v[150:153], v[224:227], v[22:25]
	v_mfma_f32_16x16x32_bf16 v[14:17], v[158:161], v[224:227], v[14:17]
	v_mfma_f32_16x16x32_bf16 v[6:9], v[150:153], v[232:235], v[6:9]
	v_mfma_f32_16x16x32_bf16 v[2:5], v[158:161], v[232:235], v[2:5]
	s_setprio 0
	s_barrier
	s_add_i32 s52, s52, 2
	s_add_u32 s12, s12, 0x100
	s_addc_u32 s13, s13, 0
	s_add_u32 s50, s50, 0x100
	s_addc_u32 s51, s51, 0
	s_cmp_gt_u32 s52, 13
	s_cbranch_scc0 .LBB0_161
	s_and_b64 vcc, exec, s[80:81]
	s_cbranch_vccz .LBB0_164
	s_barrier

; #define PG8_STAGE(bufoff, gbase, voff) do { _Pragma("unroll") for (int _i = 0; _i < 2; ++_i) \
;         __builtin_amdgcn_global_load_lds((const unsigned*)((const char*)(gbase) + (voff)[_i]), (LAS unsigned*)(lds + (bufoff) + ldsw + _i * 8192), 16, 0, 0); } while (0)
; #define PG8_LDA(dst, b, h) do { _Pragma("unroll") for (int m = 0; m < 4; ++m) _Pragma("unroll") for (int k = 0; k < 2; ++k) dst[m][k] = *(const LAS bf16x8*)(lds + PG8_SA(b, h) + aoff + m * 2048 + k * 1024); } while (0)
; #define PG8_LDB(dst, b, h) do { _Pragma("unroll") for (int n = 0; n < 2; ++n) _Pragma("unroll") for (int k = 0; k < 2; ++k) dst[n][k] = *(const LAS bf16x8*)(lds + PG8_SB(b, h) + boff + n * 2048 + k * 1024); } while (0)
; #define PG8_MMA(ai, bj, At, Bt) do { __builtin_amdgcn_s_setprio(1); _Pragma("unroll") for (int m = 0; m < 4; ++m) _Pragma("unroll") for (int n = 0; n < 2; ++n) _Pragma("unroll") for (int k = 0; k < 2; ++k) \
;         acc[ai][bj][m][n] = __builtin_amdgcn_mfma_f32_16x16x32_bf16(Bt[n][k], At[m][k], acc[ai][bj][m][n], 0, 0, 0); __builtin_amdgcn_s_setprio(0); } while (0)
; #define PG8_WAIT_V(n) asm volatile("s_waitcnt vmcnt(" #n ")" ::: "memory")
; #define PG8_WAIT_L(n) asm volatile("s_waitcnt lgkmcnt(" #n ")" ::: "memory")
; #define PG8_BAR __builtin_amdgcn_s_barrier()
; #define PG8_SCHED __builtin_amdgcn_sched_barrier(0)
; template <class Epi, bool ALIGN_EPI = true, bool SP2 = true>
; __device__ __forceinline__ void gemm_phase(LAS unsigned char* lds, const Gemm g, const Order& S, const Epi& E) {
;     ...
;         for (int t = 0; t < nt; t += 2) {
;             const bool last = (t == nt - 2);
;             const char* a1 = cA + (size_t)(t + 1) * kstep;
;             const char* a2 = last ? nA : cA + (size_t)(t + 2) * kstep; const char* b2 = last ? nB : cB + (size_t)(t + 2) * kstep;
;             const char* a3 = a2 + kstep; const char* b3 = b2 + kstep;
;             if constexpr (SP2) {
;             PG8_LDB(B0, 0, 0); PG8_LDB(B1, 0, 1); PG8_SCHED; PG8_LDA(At, 0, 0); PG8_STAGE(PG8_SA(1, 1), a1 + hstepA, voffA);
;             PG8_WAIT_V(8); PG8_WAIT_L(0); PG8_BAR; PG8_MMA(0, 0, At, B0); PG8_MMA(0, 1, At, B1); PG8_BAR; PG8_SCHED;
.LBB0_509:
	s_add_i32 s5, s19, -2
	s_add_u32 s15, s68, 0x100
	s_addc_u32 s21, s69, 0
	s_mov_b32 s24, 0
	.p2align	6
.LBB0_510:
	s_add_i32 s23, s24, 2
	s_add_u32 s68, s64, 0x100
	s_addc_u32 s69, s65, 0
	s_add_i32 s25, 0, 0x10000
	s_cmp_eq_u32 s5, s24
	s_cselect_b32 s73, s61, s69
	s_cselect_b32 s72, s60, s68
	v_add_u32_e32 v0, s25, v178
	s_cselect_b32 s71, s63, s21
	s_cselect_b32 s70, s62, s15
	s_add_i32 s34, 0, 0x14000
	ds_read_b128 v[132:135], v0
	ds_read_b128 v[136:139], v0 offset:1024
	ds_read_b128 v[170:173], v0 offset:2048
	ds_read_b128 v[174:177], v0 offset:3072
	v_add_u32_e32 v0, s34, v178
	ds_read_b128 v[180:183], v0
	ds_read_b128 v[184:187], v0 offset:1024
	ds_read_b128 v[188:191], v0 offset:2048
	ds_read_b128 v[192:195], v0 offset:3072
	v_lshl_add_u64 v[2:3], s[64:65], 0, v[166:167]
	s_add_i32 m0, s67, 0xc000
	ds_read_b128 v[196:199], v179
	ds_read_b128 v[200:203], v179 offset:1024
	ds_read_b128 v[224:227], v179 offset:2048
	ds_read_b128 v[228:231], v179 offset:3072
	ds_read_b128 v[232:235], v179 offset:4096
	ds_read_b128 v[236:239], v179 offset:5120
	ds_read_b128 v[240:243], v179 offset:6144
	ds_read_b128 v[244:247], v179 offset:7168
	global_load_lds_dwordx4 v[2:3], off
	v_lshl_add_u64 v[2:3], s[64:65], 0, v[168:169]
	s_add_i32 m0, s67, 0xe000
	s_nop 0
	global_load_lds_dwordx4 v[2:3], off
	s_waitcnt vmcnt(8)
	s_waitcnt lgkmcnt(0)
	s_barrier
	s_setprio 1
	s_waitcnt lgkmcnt(0)
	v_mfma_f32_16x16x32_bf16 v[128:131], v[132:135], v[196:199], v[128:131]
	v_mfma_f32_16x16x32_bf16 v[124:127], v[170:173], v[196:199], v[124:127]
	v_mfma_f32_16x16x32_bf16 v[120:123], v[132:135], v[224:227], v[120:123]
	v_mfma_f32_16x16x32_bf16 v[116:119], v[170:173], v[224:227], v[116:119]
	v_mfma_f32_16x16x32_bf16 v[112:115], v[132:135], v[232:235], v[112:115]
	v_mfma_f32_16x16x32_bf16 v[108:111], v[170:173], v[232:235], v[108:111]
	v_mfma_f32_16x16x32_bf16 v[104:107], v[132:135], v[240:243], v[104:107]
	v_mfma_f32_16x16x32_bf16 v[100:103], v[170:173], v[240:243], v[100:103]
	v_mfma_f32_16x16x32_bf16 v[128:131], v[136:139], v[200:203], v[128:131]
	v_mfma_f32_16x16x32_bf16 v[124:127], v[174:177], v[200:203], v[124:127]
	v_mfma_f32_16x16x32_bf16 v[120:123], v[136:139], v[228:231], v[120:123]
	v_mfma_f32_16x16x32_bf16 v[116:119], v[174:177], v[228:231], v[116:119]
	v_mfma_f32_16x16x32_bf16 v[112:115], v[136:139], v[236:239], v[112:115]
	v_mfma_f32_16x16x32_bf16 v[108:111], v[174:177], v[236:239], v[108:111]
	v_mfma_f32_16x16x32_bf16 v[104:107], v[136:139], v[244:247], v[104:107]
	v_mfma_f32_16x16x32_bf16 v[100:103], v[174:177], v[244:247], v[100:103]
	s_setprio 0
	s_setprio 1
	v_mfma_f32_16x16x32_bf16 v[96:99], v[180:183], v[196:199], v[96:99]
	v_mfma_f32_16x16x32_bf16 v[92:95], v[188:191], v[196:199], v[92:95]
	v_mfma_f32_16x16x32_bf16 v[88:91], v[180:183], v[224:227], v[88:91]
	v_mfma_f32_16x16x32_bf16 v[84:87], v[188:191], v[224:227], v[84:87]
	v_mfma_f32_16x16x32_bf16 v[80:83], v[180:183], v[232:235], v[80:83]
	v_mfma_f32_16x16x32_bf16 v[76:79], v[188:191], v[232:235], v[76:79]
	v_mfma_f32_16x16x32_bf16 v[72:75], v[180:183], v[240:243], v[72:75]
	v_mfma_f32_16x16x32_bf16 v[68:71], v[188:191], v[240:243], v[68:71]
	v_mfma_f32_16x16x32_bf16 v[96:99], v[184:187], v[200:203], v[96:99]
	v_mfma_f32_16x16x32_bf16 v[92:95], v[192:195], v[200:203], v[92:95]
	v_mfma_f32_16x16x32_bf16 v[88:91], v[184:187], v[228:231], v[88:91]
	v_mfma_f32_16x16x32_bf16 v[84:87], v[192:195], v[228:231], v[84:87]
	v_mfma_f32_16x16x32_bf16 v[80:83], v[184:187], v[236:239], v[80:83]
	v_mfma_f32_16x16x32_bf16 v[76:79], v[192:195], v[236:239], v[76:79]
	v_mfma_f32_16x16x32_bf16 v[72:75], v[184:187], v[244:247], v[72:75]
	v_mfma_f32_16x16x32_bf16 v[68:71], v[192:195], v[244:247], v[68:71]
	s_setprio 0
	s_barrier
	s_add_i32 s24, s25, s76
	v_lshl_add_u64 v[248:249], s[70:71], 0, v[142:143]
	s_mov_b32 m0, s24
	ds_read_b128 v[196:199], v179 offset:16384
	ds_read_b128 v[200:203], v179 offset:17408
	ds_read_b128 v[224:227], v179 offset:18432
	ds_read_b128 v[228:231], v179 offset:19456
	ds_read_b128 v[232:235], v179 offset:20480
	ds_read_b128 v[236:239], v179 offset:21504
	ds_read_b128 v[240:243], v179 offset:22528
	ds_read_b128 v[244:247], v179 offset:23552
	global_load_lds_dwordx4 v[248:249], off
	s_add_i32 m0, s24, 0x2000
	s_add_u32 s24, s70, 0x40000
	v_lshl_add_u64 v[250:251], s[70:71], 0, v[146:147]
	s_addc_u32 s25, s71, 0
	s_add_i32 s34, s34, s76
	global_load_lds_dwordx4 v[250:251], off
	v_lshl_add_u64 v[2:3], s[24:25], 0, v[142:143]
	s_mov_b32 m0, s34
	v_lshl_add_u64 v[252:253], s[72:73], 0, v[140:141]
	global_load_lds_dwordx4 v[2:3], off
	v_lshl_add_u64 v[2:3], s[24:25], 0, v[146:147]
	s_add_i32 m0, s34, 0x2000
	v_lshl_add_u64 v[210:211], s[72:73], 0, v[144:145]
	global_load_lds_dwordx4 v[2:3], off
	s_mov_b32 m0, s67
	s_nop 0
	global_load_lds_dwordx4 v[252:253], off
	s_mov_b32 m0, s83
	s_nop 0
	global_load_lds_dwordx4 v[210:211], off
	s_waitcnt vmcnt(8)
	s_waitcnt lgkmcnt(0)
	s_barrier
; #define PG8_STAGE(bufoff, gbase, voff) do { _Pragma("unroll") for (int _i = 0; _i < 2; ++_i) \
;         __builtin_amdgcn_global_load_lds((const unsigned*)((const char*)(gbase) + (voff)[_i]), (LAS unsigned*)(lds + (bufoff) + ldsw + _i * 8192), 16, 0, 0); } while (0)
; #define PG8_LDA(dst, b, h) do { _Pragma("unroll") for (int m = 0; m < 4; ++m) _Pragma("unroll") for (int k = 0; k < 2; ++k) dst[m][k] = *(const LAS bf16x8*)(lds + PG8_SA(b, h) + aoff + m * 2048 + k * 1024); } while (0)
; #define PG8_LDB(dst, b, h) do { _Pragma("unroll") for (int n = 0; n < 2; ++n) _Pragma("unroll") for (int k = 0; k < 2; ++k) dst[n][k] = *(const LAS bf16x8*)(lds + PG8_SB(b, h) + boff + n * 2048 + k * 1024); } while (0)
; #define PG8_MMA(ai, bj, At, Bt) do { __builtin_amdgcn_s_setprio(1); _Pragma("unroll") for (int m = 0; m < 4; ++m) _Pragma("unroll") for (int n = 0; n < 2; ++n) _Pragma("unroll") for (int k = 0; k < 2; ++k) \
;         acc[ai][bj][m][n] = __builtin_amdgcn_mfma_f32_16x16x32_bf16(Bt[n][k], At[m][k], acc[ai][bj][m][n], 0, 0, 0); __builtin_amdgcn_s_setprio(0); } while (0)
; #define PG8_WAIT_V(n) asm volatile("s_waitcnt vmcnt(" #n ")" ::: "memory")
; #define PG8_WAIT_L(n) asm volatile("s_waitcnt lgkmcnt(" #n ")" ::: "memory")
; #define PG8_BAR __builtin_amdgcn_s_barrier()
; #define PG8_SCHED __builtin_amdgcn_sched_barrier(0)
; template <class Epi, bool ALIGN_EPI = true, bool SP2 = true>
; __device__ __forceinline__ void gemm_phase(LAS unsigned char* lds, const Gemm g, const Order& S, const Epi& E) {
;     ...
;             PG8_WAIT_V(8); PG8_WAIT_L(0); PG8_BAR; PG8_MMA(0, 0, At, B0); PG8_MMA(0, 1, At, B1); PG8_BAR; PG8_SCHED;
;             PG8_LDA(At, 0, 1); PG8_STAGE(PG8_SB(0, 0), b2, voffB); PG8_STAGE(PG8_SB(0, 1), b2 + hstepB, voffB); PG8_STAGE(PG8_SA(0, 0), a2, voffA);
;             PG8_WAIT_V(8); PG8_WAIT_L(0); PG8_BAR; PG8_MMA(1, 0, At, B0); PG8_MMA(1, 1, At, B1); PG8_BAR; PG8_SCHED;
;             PG8_LDB(B0, 1, 0); PG8_LDB(B1, 1, 1); PG8_SCHED; PG8_LDA(At, 1, 0); PG8_STAGE(PG8_SA(0, 1), a2 + hstepA, voffA);
;             PG8_WAIT_V(8); PG8_WAIT_L(0); PG8_BAR; PG8_MMA(0, 0, At, B0); PG8_MMA(0, 1, At, B1); PG8_BAR; PG8_SCHED;
	s_setprio 1
	s_waitcnt lgkmcnt(0)
	v_mfma_f32_16x16x32_bf16 v[64:67], v[132:135], v[196:199], v[64:67]
	v_mfma_f32_16x16x32_bf16 v[60:63], v[170:173], v[196:199], v[60:63]
	v_mfma_f32_16x16x32_bf16 v[56:59], v[132:135], v[224:227], v[56:59]
	v_mfma_f32_16x16x32_bf16 v[52:55], v[170:173], v[224:227], v[52:55]
	v_mfma_f32_16x16x32_bf16 v[48:51], v[132:135], v[232:235], v[48:51]
	v_mfma_f32_16x16x32_bf16 v[44:47], v[170:173], v[232:235], v[44:47]
	v_mfma_f32_16x16x32_bf16 v[40:43], v[132:135], v[240:243], v[40:43]
	v_mfma_f32_16x16x32_bf16 v[36:39], v[170:173], v[240:243], v[36:39]
	v_mfma_f32_16x16x32_bf16 v[64:67], v[136:139], v[200:203], v[64:67]
	v_mfma_f32_16x16x32_bf16 v[60:63], v[174:177], v[200:203], v[60:63]
	v_mfma_f32_16x16x32_bf16 v[56:59], v[136:139], v[228:231], v[56:59]
	v_mfma_f32_16x16x32_bf16 v[52:55], v[174:177], v[228:231], v[52:55]
	v_mfma_f32_16x16x32_bf16 v[48:51], v[136:139], v[236:239], v[48:51]
	v_mfma_f32_16x16x32_bf16 v[44:47], v[174:177], v[236:239], v[44:47]
	v_mfma_f32_16x16x32_bf16 v[40:43], v[136:139], v[244:247], v[40:43]
	v_mfma_f32_16x16x32_bf16 v[36:39], v[174:177], v[244:247], v[36:39]
	s_setprio 0
	s_setprio 1
	v_mfma_f32_16x16x32_bf16 v[32:35], v[180:183], v[196:199], v[32:35]
	v_mfma_f32_16x16x32_bf16 v[28:31], v[188:191], v[196:199], v[28:31]
	v_mfma_f32_16x16x32_bf16 v[24:27], v[180:183], v[224:227], v[24:27]
	v_mfma_f32_16x16x32_bf16 v[20:23], v[188:191], v[224:227], v[20:23]
	v_mfma_f32_16x16x32_bf16 v[16:19], v[180:183], v[232:235], v[16:19]
	v_mfma_f32_16x16x32_bf16 v[12:15], v[188:191], v[232:235], v[12:15]
	v_mfma_f32_16x16x32_bf16 v[8:11], v[180:183], v[240:243], v[8:11]
	v_mfma_f32_16x16x32_bf16 v[2:5], v[188:191], v[240:243], v[4:7]
	v_mfma_f32_16x16x32_bf16 v[32:35], v[184:187], v[200:203], v[32:35]
	v_mfma_f32_16x16x32_bf16 v[28:31], v[192:195], v[200:203], v[28:31]
	v_mfma_f32_16x16x32_bf16 v[24:27], v[184:187], v[228:231], v[24:27]
	v_mfma_f32_16x16x32_bf16 v[20:23], v[192:195], v[228:231], v[20:23]
	v_mfma_f32_16x16x32_bf16 v[16:19], v[184:187], v[236:239], v[16:19]
	v_mfma_f32_16x16x32_bf16 v[12:15], v[192:195], v[236:239], v[12:15]
	v_mfma_f32_16x16x32_bf16 v[8:11], v[184:187], v[244:247], v[8:11]
	v_mfma_f32_16x16x32_bf16 v[2:5], v[192:195], v[244:247], v[2:5]
	s_setprio 0
	s_barrier
	s_add_i32 s34, 0, 0x18000
	v_add_u32_e32 v0, s34, v178
	s_add_i32 s35, 0, 0x1c000
	ds_read_b128 v[132:135], v0
	ds_read_b128 v[136:139], v0 offset:1024
	ds_read_b128 v[170:173], v0 offset:2048
	ds_read_b128 v[174:177], v0 offset:3072
	v_add_u32_e32 v0, s35, v178
	ds_read_b128 v[180:183], v0
	ds_read_b128 v[184:187], v0 offset:1024
	ds_read_b128 v[188:191], v0 offset:2048
	ds_read_b128 v[192:195], v0 offset:3072
	s_add_u32 s24, s72, 0x140000
	s_addc_u32 s25, s73, 0
	s_mov_b32 m0, s84
	v_lshl_add_u64 v[6:7], s[24:25], 0, v[140:141]
	ds_read_b128 v[196:199], v179 offset:32768
	ds_read_b128 v[200:203], v179 offset:33792
	ds_read_b128 v[224:227], v179 offset:34816
	ds_read_b128 v[228:231], v179 offset:35840
	ds_read_b128 v[232:235], v179 offset:36864
	ds_read_b128 v[236:239], v179 offset:37888
	ds_read_b128 v[240:243], v179 offset:38912
	ds_read_b128 v[244:247], v179 offset:39936
	global_load_lds_dwordx4 v[6:7], off
	v_lshl_add_u64 v[6:7], s[24:25], 0, v[144:145]
	s_mov_b32 m0, s85
	s_nop 0
	global_load_lds_dwordx4 v[6:7], off
	s_waitcnt vmcnt(8)
	s_waitcnt lgkmcnt(0)
	s_barrier
	s_setprio 1
	s_waitcnt lgkmcnt(0)
	v_mfma_f32_16x16x32_bf16 v[128:131], v[132:135], v[196:199], v[128:131]
	v_mfma_f32_16x16x32_bf16 v[124:127], v[170:173], v[196:199], v[124:127]
	v_mfma_f32_16x16x32_bf16 v[120:123], v[132:135], v[224:227], v[120:123]
	v_mfma_f32_16x16x32_bf16 v[116:119], v[170:173], v[224:227], v[116:119]
	v_mfma_f32_16x16x32_bf16 v[112:115], v[132:135], v[232:235], v[112:115]
	v_mfma_f32_16x16x32_bf16 v[108:111], v[170:173], v[232:235], v[108:111]
	v_mfma_f32_16x16x32_bf16 v[104:107], v[132:135], v[240:243], v[104:107]
	v_mfma_f32_16x16x32_bf16 v[100:103], v[170:173], v[240:243], v[100:103]
	v_mfma_f32_16x16x32_bf16 v[128:131], v[136:139], v[200:203], v[128:131]
	v_mfma_f32_16x16x32_bf16 v[124:127], v[174:177], v[200:203], v[124:127]
	v_mfma_f32_16x16x32_bf16 v[120:123], v[136:139], v[228:231], v[120:123]
	v_mfma_f32_16x16x32_bf16 v[116:119], v[174:177], v[228:231], v[116:119]
	v_mfma_f32_16x16x32_bf16 v[112:115], v[136:139], v[236:239], v[112:115]
	v_mfma_f32_16x16x32_bf16 v[108:111], v[174:177], v[236:239], v[108:111]
	v_mfma_f32_16x16x32_bf16 v[104:107], v[136:139], v[244:247], v[104:107]
	v_mfma_f32_16x16x32_bf16 v[100:103], v[174:177], v[244:247], v[100:103]
	s_setprio 0
	s_setprio 1
	v_mfma_f32_16x16x32_bf16 v[96:99], v[180:183], v[196:199], v[96:99]
	v_mfma_f32_16x16x32_bf16 v[92:95], v[188:191], v[196:199], v[92:95]
	v_mfma_f32_16x16x32_bf16 v[88:91], v[180:183], v[224:227], v[88:91]
	v_mfma_f32_16x16x32_bf16 v[84:87], v[188:191], v[224:227], v[84:87]
	v_mfma_f32_16x16x32_bf16 v[80:83], v[180:183], v[232:235], v[80:83]
	v_mfma_f32_16x16x32_bf16 v[76:79], v[188:191], v[232:235], v[76:79]
	v_mfma_f32_16x16x32_bf16 v[72:75], v[180:183], v[240:243], v[72:75]
	v_mfma_f32_16x16x32_bf16 v[68:71], v[188:191], v[240:243], v[68:71]
	v_mfma_f32_16x16x32_bf16 v[96:99], v[184:187], v[200:203], v[96:99]
	v_mfma_f32_16x16x32_bf16 v[92:95], v[192:195], v[200:203], v[92:95]
	v_mfma_f32_16x16x32_bf16 v[88:91], v[184:187], v[228:231], v[88:91]
	v_mfma_f32_16x16x32_bf16 v[84:87], v[192:195], v[228:231], v[84:87]
	v_mfma_f32_16x16x32_bf16 v[80:83], v[184:187], v[236:239], v[80:83]
	v_mfma_f32_16x16x32_bf16 v[76:79], v[192:195], v[236:239], v[76:79]
	v_mfma_f32_16x16x32_bf16 v[72:75], v[184:187], v[244:247], v[72:75]
	v_mfma_f32_16x16x32_bf16 v[68:71], v[192:195], v[244:247], v[68:71]
	s_setprio 0
	s_barrier
; #define PG8_STAGE(bufoff, gbase, voff) do { _Pragma("unroll") for (int _i = 0; _i < 2; ++_i) \
;         __builtin_amdgcn_global_load_lds((const unsigned*)((const char*)(gbase) + (voff)[_i]), (LAS unsigned*)(lds + (bufoff) + ldsw + _i * 8192), 16, 0, 0); } while (0)
; #define PG8_LDA(dst, b, h) do { _Pragma("unroll") for (int m = 0; m < 4; ++m) _Pragma("unroll") for (int k = 0; k < 2; ++k) dst[m][k] = *(const LAS bf16x8*)(lds + PG8_SA(b, h) + aoff + m * 2048 + k * 1024); } while (0)
; #define PG8_MMA(ai, bj, At, Bt) do { __builtin_amdgcn_s_setprio(1); _Pragma("unroll") for (int m = 0; m < 4; ++m) _Pragma("unroll") for (int n = 0; n < 2; ++n) _Pragma("unroll") for (int k = 0; k < 2; ++k) \
;         acc[ai][bj][m][n] = __builtin_amdgcn_mfma_f32_16x16x32_bf16(Bt[n][k], At[m][k], acc[ai][bj][m][n], 0, 0, 0); __builtin_amdgcn_s_setprio(0); } while (0)
; #define PG8_WAIT_V(n) asm volatile("s_waitcnt vmcnt(" #n ")" ::: "memory")
; #define PG8_WAIT_L(n) asm volatile("s_waitcnt lgkmcnt(" #n ")" ::: "memory")
; #define PG8_BAR __builtin_amdgcn_s_barrier()
; #define PG8_SCHED __builtin_amdgcn_sched_barrier(0)
; template <class Epi, bool ALIGN_EPI = true, bool SP2 = true>
; __device__ __forceinline__ void gemm_phase(LAS unsigned char* lds, const Gemm g, const Order& S, const Epi& E) {
;     ...
;             PG8_WAIT_V(8); PG8_WAIT_L(0); PG8_BAR; PG8_MMA(0, 0, At, B0); PG8_MMA(0, 1, At, B1); PG8_BAR; PG8_SCHED;
;             PG8_LDA(At, 1, 1); PG8_STAGE(PG8_SB(1, 0), b3, voffB); PG8_STAGE(PG8_SB(1, 1), b3 + hstepB, voffB); PG8_STAGE(PG8_SA(1, 0), a3, voffA);
;             PG8_WAIT_V(8); PG8_WAIT_L(0); PG8_BAR; PG8_MMA(1, 0, At, B0); PG8_MMA(1, 1, At, B1); PG8_BAR; PG8_SCHED;
	s_add_i32 s24, s34, s76
	v_lshl_add_u64 v[6:7], v[248:249], 0, s[26:27]
	s_mov_b32 m0, s24
	ds_read_b128 v[196:199], v179 offset:49152
	ds_read_b128 v[200:203], v179 offset:50176
	ds_read_b128 v[224:227], v179 offset:51200
	ds_read_b128 v[228:231], v179 offset:52224
	ds_read_b128 v[232:235], v179 offset:53248
	ds_read_b128 v[236:239], v179 offset:54272
	ds_read_b128 v[240:243], v179 offset:55296
	ds_read_b128 v[244:247], v179 offset:56320
	global_load_lds_dwordx4 v[6:7], off
	s_add_i32 m0, s24, 0x2000
	s_add_u32 s24, s70, 0x40080
	v_lshl_add_u64 v[6:7], v[250:251], 0, s[26:27]
	s_addc_u32 s25, s71, 0
	s_add_i32 s34, s35, s76
	global_load_lds_dwordx4 v[6:7], off
	v_lshl_add_u64 v[6:7], s[24:25], 0, v[142:143]
	s_mov_b32 m0, s34
	s_nop 0
	global_load_lds_dwordx4 v[6:7], off
	v_lshl_add_u64 v[6:7], s[24:25], 0, v[146:147]
	s_add_i32 m0, s34, 0x2000
	s_nop 0
	global_load_lds_dwordx4 v[6:7], off
	v_lshl_add_u64 v[6:7], v[252:253], 0, s[26:27]
	s_mov_b32 m0, s88
	s_nop 0
	global_load_lds_dwordx4 v[6:7], off
	v_lshl_add_u64 v[6:7], v[210:211], 0, s[26:27]
	s_mov_b32 m0, s89
	s_nop 0
	global_load_lds_dwordx4 v[6:7], off
	s_waitcnt vmcnt(8)
	s_waitcnt lgkmcnt(0)
	s_barrier
	s_setprio 1
	s_waitcnt lgkmcnt(0)
	v_mfma_f32_16x16x32_bf16 v[64:67], v[132:135], v[196:199], v[64:67]
	v_mfma_f32_16x16x32_bf16 v[60:63], v[170:173], v[196:199], v[60:63]
	v_mfma_f32_16x16x32_bf16 v[56:59], v[132:135], v[224:227], v[56:59]
	v_mfma_f32_16x16x32_bf16 v[52:55], v[170:173], v[224:227], v[52:55]
	v_mfma_f32_16x16x32_bf16 v[48:51], v[132:135], v[232:235], v[48:51]
	v_mfma_f32_16x16x32_bf16 v[44:47], v[170:173], v[232:235], v[44:47]
	v_mfma_f32_16x16x32_bf16 v[40:43], v[132:135], v[240:243], v[40:43]
	v_mfma_f32_16x16x32_bf16 v[36:39], v[170:173], v[240:243], v[36:39]
	v_mfma_f32_16x16x32_bf16 v[64:67], v[136:139], v[200:203], v[64:67]
	v_mfma_f32_16x16x32_bf16 v[60:63], v[174:177], v[200:203], v[60:63]
	v_mfma_f32_16x16x32_bf16 v[56:59], v[136:139], v[228:231], v[56:59]
	v_mfma_f32_16x16x32_bf16 v[52:55], v[174:177], v[228:231], v[52:55]
	v_mfma_f32_16x16x32_bf16 v[48:51], v[136:139], v[236:239], v[48:51]
	v_mfma_f32_16x16x32_bf16 v[44:47], v[174:177], v[236:239], v[44:47]
	v_mfma_f32_16x16x32_bf16 v[40:43], v[136:139], v[244:247], v[40:43]
	v_mfma_f32_16x16x32_bf16 v[36:39], v[174:177], v[244:247], v[36:39]
	s_setprio 0
	s_setprio 1
	v_mfma_f32_16x16x32_bf16 v[32:35], v[180:183], v[196:199], v[32:35]
	v_mfma_f32_16x16x32_bf16 v[28:31], v[188:191], v[196:199], v[28:31]
	v_mfma_f32_16x16x32_bf16 v[24:27], v[180:183], v[224:227], v[24:27]
	v_mfma_f32_16x16x32_bf16 v[20:23], v[188:191], v[224:227], v[20:23]
	v_mfma_f32_16x16x32_bf16 v[16:19], v[180:183], v[232:235], v[16:19]
	v_mfma_f32_16x16x32_bf16 v[12:15], v[188:191], v[232:235], v[12:15]
	v_mfma_f32_16x16x32_bf16 v[6:9], v[180:183], v[240:243], v[8:11]
	v_mfma_f32_16x16x32_bf16 v[2:5], v[188:191], v[240:243], v[2:5]
	v_mfma_f32_16x16x32_bf16 v[32:35], v[184:187], v[200:203], v[32:35]
	v_mfma_f32_16x16x32_bf16 v[28:31], v[192:195], v[200:203], v[28:31]
	v_mfma_f32_16x16x32_bf16 v[24:27], v[184:187], v[228:231], v[24:27]
	v_mfma_f32_16x16x32_bf16 v[20:23], v[192:195], v[228:231], v[20:23]
	v_mfma_f32_16x16x32_bf16 v[16:19], v[184:187], v[236:239], v[16:19]
	v_mfma_f32_16x16x32_bf16 v[12:15], v[192:195], v[236:239], v[12:15]
	v_mfma_f32_16x16x32_bf16 v[8:11], v[184:187], v[244:247], v[6:9]
	v_mfma_f32_16x16x32_bf16 v[4:7], v[192:195], v[244:247], v[2:5]
	s_setprio 0
	s_barrier
	s_add_u32 s15, s15, 0x100
	s_addc_u32 s21, s21, 0
	s_cmp_ge_i32 s23, s19
	s_mov_b64 s[64:65], s[68:69]
	s_mov_b32 s24, s23
	s_cbranch_scc0 .LBB0_510

; #define PG8_STAGE(bufoff, gbase, voff) do { _Pragma("unroll") for (int _i = 0; _i < 2; ++_i) \
;         __builtin_amdgcn_global_load_lds((const unsigned*)((const char*)(gbase) + (voff)[_i]), (LAS unsigned*)(lds + (bufoff) + ldsw + _i * 8192), 16, 0, 0); } while (0)
; #define PG8_LDA(dst, b, h) do { _Pragma("unroll") for (int m = 0; m < 4; ++m) _Pragma("unroll") for (int k = 0; k < 2; ++k) dst[m][k] = *(const LAS bf16x8*)(lds + PG8_SA(b, h) + aoff + m * 2048 + k * 1024); } while (0)
; #define PG8_LDB(dst, b, h) do { _Pragma("unroll") for (int n = 0; n < 2; ++n) _Pragma("unroll") for (int k = 0; k < 2; ++k) dst[n][k] = *(const LAS bf16x8*)(lds + PG8_SB(b, h) + boff + n * 2048 + k * 1024); } while (0)
; #define PG8_MMA(ai, bj, At, Bt) do { __builtin_amdgcn_s_setprio(1); _Pragma("unroll") for (int m = 0; m < 4; ++m) _Pragma("unroll") for (int n = 0; n < 2; ++n) _Pragma("unroll") for (int k = 0; k < 2; ++k) \
;         acc[ai][bj][m][n] = __builtin_amdgcn_mfma_f32_16x16x32_bf16(Bt[n][k], At[m][k], acc[ai][bj][m][n], 0, 0, 0); __builtin_amdgcn_s_setprio(0); } while (0)
; #define PG8_WAIT_V(n) asm volatile("s_waitcnt vmcnt(" #n ")" ::: "memory")
; #define PG8_WAIT_L(n) asm volatile("s_waitcnt lgkmcnt(" #n ")" ::: "memory")
; #define PG8_BAR __builtin_amdgcn_s_barrier()
; template <class Epi, bool ALIGN_EPI = true, bool SP2 = true>
; __device__ __forceinline__ void gemm_phase(LAS unsigned char* lds, const Gemm g, const Order& S, const Epi& E) {
;     ...
;         for (int t = 0; t < nt; t += 2) {
;             const bool last = (t == nt - 2);
;             const char* a1 = cA + (size_t)(t + 1) * kstep;
;             const char* a2 = last ? nA : cA + (size_t)(t + 2) * kstep; const char* b2 = last ? nB : cB + (size_t)(t + 2) * kstep;
;             const char* a3 = a2 + kstep; const char* b3 = b2 + kstep;
;             if constexpr (SP2) {
;             PG8_LDB(B0, 0, 0); PG8_LDB(B1, 0, 1); PG8_SCHED; PG8_LDA(At, 0, 0); PG8_STAGE(PG8_SA(1, 1), a1 + hstepA, voffA);
;             PG8_WAIT_V(8); PG8_WAIT_L(0); PG8_BAR; PG8_MMA(0, 0, At, B0); PG8_MMA(0, 1, At, B1); PG8_BAR; PG8_SCHED;
;     ...
;         for (int a = 0; a < 2; ++a)
; #pragma unroll
;             for (int b = 0; b < 2; ++b)
; #pragma unroll
;                 for (int m = 0; m < 4; ++m)
; #pragma unroll
;                     for (int n = 0; n < 2; ++n) acc[a][b][m][n] = (f32x4){0.f, 0.f, 0.f, 0.f};
.LBB0_723:
	s_add_i32 s13, s54, -2
	s_add_u32 s15, s68, 0x100
	v_mov_b32_e32 v2, 0
	s_addc_u32 s55, s69, 0
	s_mov_b32 s57, 0
	v_mov_b32_e32 v3, v2
	v_mov_b32_e32 v4, v2
	v_mov_b32_e32 v5, v2
	v_mov_b32_e32 v6, v2
	v_mov_b32_e32 v7, v2
	v_mov_b32_e32 v8, v2
	v_mov_b32_e32 v9, v2
	v_mov_b32_e32 v18, v2
	v_mov_b32_e32 v19, v2
	v_mov_b32_e32 v20, v2
	v_mov_b32_e32 v21, v2
	v_mov_b32_e32 v22, v2
	v_mov_b32_e32 v23, v2
	v_mov_b32_e32 v24, v2
	v_mov_b32_e32 v25, v2
	v_mov_b32_e32 v34, v2
	v_mov_b32_e32 v35, v2
	v_mov_b32_e32 v36, v2
	v_mov_b32_e32 v37, v2
	v_mov_b32_e32 v38, v2
	v_mov_b32_e32 v39, v2
	v_mov_b32_e32 v40, v2
	v_mov_b32_e32 v41, v2
	v_mov_b32_e32 v50, v2
	v_mov_b32_e32 v51, v2
	v_mov_b32_e32 v52, v2
	v_mov_b32_e32 v53, v2
	v_mov_b32_e32 v54, v2
	v_mov_b32_e32 v55, v2
	v_mov_b32_e32 v56, v2
	v_mov_b32_e32 v57, v2
	v_mov_b32_e32 v10, v2
	v_mov_b32_e32 v11, v2
	v_mov_b32_e32 v12, v2
	v_mov_b32_e32 v13, v2
	v_mov_b32_e32 v14, v2
	v_mov_b32_e32 v15, v2
	v_mov_b32_e32 v16, v2
	v_mov_b32_e32 v17, v2
	v_mov_b32_e32 v26, v2
	v_mov_b32_e32 v27, v2
	v_mov_b32_e32 v28, v2
	v_mov_b32_e32 v29, v2
	v_mov_b32_e32 v30, v2
	v_mov_b32_e32 v31, v2
	v_mov_b32_e32 v32, v2
	v_mov_b32_e32 v33, v2
	v_mov_b32_e32 v42, v2
	v_mov_b32_e32 v43, v2
	v_mov_b32_e32 v44, v2
	v_mov_b32_e32 v45, v2
	v_mov_b32_e32 v46, v2
	v_mov_b32_e32 v47, v2
	v_mov_b32_e32 v48, v2
	v_mov_b32_e32 v49, v2
	v_mov_b32_e32 v58, v2
	v_mov_b32_e32 v59, v2
	v_mov_b32_e32 v60, v2
	v_mov_b32_e32 v61, v2
	v_mov_b32_e32 v62, v2
	v_mov_b32_e32 v63, v2
	v_mov_b32_e32 v64, v2
	v_mov_b32_e32 v65, v2
	v_mov_b32_e32 v66, v2
	v_mov_b32_e32 v67, v2
	v_mov_b32_e32 v68, v2
	v_mov_b32_e32 v69, v2
	v_mov_b32_e32 v70, v2
	v_mov_b32_e32 v71, v2
	v_mov_b32_e32 v72, v2
	v_mov_b32_e32 v73, v2
	v_mov_b32_e32 v82, v2
	v_mov_b32_e32 v83, v2
	v_mov_b32_e32 v84, v2
	v_mov_b32_e32 v85, v2
	v_mov_b32_e32 v86, v2
	v_mov_b32_e32 v87, v2
	v_mov_b32_e32 v88, v2
	v_mov_b32_e32 v89, v2
	v_mov_b32_e32 v98, v2
	v_mov_b32_e32 v99, v2
	v_mov_b32_e32 v100, v2
	v_mov_b32_e32 v101, v2
	v_mov_b32_e32 v102, v2
	v_mov_b32_e32 v103, v2
	v_mov_b32_e32 v104, v2
	v_mov_b32_e32 v105, v2
	v_mov_b32_e32 v114, v2
	v_mov_b32_e32 v115, v2
	v_mov_b32_e32 v116, v2
	v_mov_b32_e32 v117, v2
	v_mov_b32_e32 v118, v2
	v_mov_b32_e32 v119, v2
	v_mov_b32_e32 v120, v2
	v_mov_b32_e32 v121, v2
	v_mov_b32_e32 v74, v2
	v_mov_b32_e32 v75, v2
	v_mov_b32_e32 v76, v2
	v_mov_b32_e32 v77, v2
	v_mov_b32_e32 v78, v2
	v_mov_b32_e32 v79, v2
	v_mov_b32_e32 v80, v2
	v_mov_b32_e32 v81, v2
	v_mov_b32_e32 v90, v2
	v_mov_b32_e32 v91, v2
	v_mov_b32_e32 v92, v2
	v_mov_b32_e32 v93, v2
	v_mov_b32_e32 v94, v2
	v_mov_b32_e32 v95, v2
	v_mov_b32_e32 v96, v2
	v_mov_b32_e32 v97, v2
	v_mov_b32_e32 v106, v2
	v_mov_b32_e32 v107, v2
	v_mov_b32_e32 v108, v2
	v_mov_b32_e32 v109, v2
	v_mov_b32_e32 v110, v2
	v_mov_b32_e32 v111, v2
	v_mov_b32_e32 v112, v2
	v_mov_b32_e32 v113, v2
	v_mov_b32_e32 v122, v2
	v_mov_b32_e32 v123, v2
	v_mov_b32_e32 v124, v2
	v_mov_b32_e32 v125, v2
	v_mov_b32_e32 v126, v2
	v_mov_b32_e32 v127, v2
	v_mov_b32_e32 v128, v2
	v_mov_b32_e32 v129, v2
	.p2align	6
.LBB0_724:
	s_add_i32 s63, s57, 2
	s_add_u32 s68, s66, 0x100
	s_addc_u32 s69, s67, 0
	s_add_i32 s65, 0, 0x10000
	s_cmp_eq_u32 s13, s57
	s_cselect_b32 s73, s59, s69
	s_cselect_b32 s72, s58, s68
	v_add_u32_e32 v158, s65, v160
	s_cselect_b32 s71, s61, s55
	s_cselect_b32 s70, s60, s15
	s_add_i32 s57, 0, 0x14000
	ds_read_b128 v[162:165], v158
	ds_read_b128 v[166:169], v158 offset:1024
	ds_read_b128 v[170:173], v158 offset:2048
	ds_read_b128 v[174:177], v158 offset:3072
	v_add_u32_e32 v158, s57, v160
	ds_read_b128 v[178:181], v158
	ds_read_b128 v[182:185], v158 offset:1024
	ds_read_b128 v[186:189], v158 offset:2048
	ds_read_b128 v[190:193], v158 offset:3072
	v_lshl_add_u64 v[158:159], s[66:67], 0, v[154:155]
	s_add_i32 m0, s35, 0xc000
	ds_read_b128 v[194:197], v161
	ds_read_b128 v[198:201], v161 offset:1024
	ds_read_b128 v[224:227], v161 offset:2048
	ds_read_b128 v[228:231], v161 offset:3072
	ds_read_b128 v[232:235], v161 offset:4096
	ds_read_b128 v[236:239], v161 offset:5120
	ds_read_b128 v[240:243], v161 offset:6144
	ds_read_b128 v[244:247], v161 offset:7168
	global_load_lds_dwordx4 v[158:159], off
	v_lshl_add_u64 v[158:159], s[66:67], 0, v[156:157]
	s_add_i32 m0, s35, 0xe000
	s_nop 0
	global_load_lds_dwordx4 v[158:159], off
	s_waitcnt vmcnt(8)
	s_waitcnt lgkmcnt(0)
	s_barrier
	s_setprio 1
	s_waitcnt lgkmcnt(0)
	v_mfma_f32_16x16x32_bf16 v[126:129], v[162:165], v[194:197], v[126:129]
	v_mfma_f32_16x16x32_bf16 v[122:125], v[170:173], v[194:197], v[122:125]
	v_mfma_f32_16x16x32_bf16 v[110:113], v[162:165], v[224:227], v[110:113]
	v_mfma_f32_16x16x32_bf16 v[106:109], v[170:173], v[224:227], v[106:109]
	v_mfma_f32_16x16x32_bf16 v[94:97], v[162:165], v[232:235], v[94:97]
	v_mfma_f32_16x16x32_bf16 v[90:93], v[170:173], v[232:235], v[90:93]
	v_mfma_f32_16x16x32_bf16 v[78:81], v[162:165], v[240:243], v[78:81]
	v_mfma_f32_16x16x32_bf16 v[74:77], v[170:173], v[240:243], v[74:77]
	v_mfma_f32_16x16x32_bf16 v[126:129], v[166:169], v[198:201], v[126:129]
	v_mfma_f32_16x16x32_bf16 v[122:125], v[174:177], v[198:201], v[122:125]
	v_mfma_f32_16x16x32_bf16 v[110:113], v[166:169], v[228:231], v[110:113]
	v_mfma_f32_16x16x32_bf16 v[106:109], v[174:177], v[228:231], v[106:109]
	v_mfma_f32_16x16x32_bf16 v[94:97], v[166:169], v[236:239], v[94:97]
	v_mfma_f32_16x16x32_bf16 v[90:93], v[174:177], v[236:239], v[90:93]
	v_mfma_f32_16x16x32_bf16 v[78:81], v[166:169], v[244:247], v[78:81]
	v_mfma_f32_16x16x32_bf16 v[74:77], v[174:177], v[244:247], v[74:77]
	s_setprio 0
	s_setprio 1
	v_mfma_f32_16x16x32_bf16 v[118:121], v[178:181], v[194:197], v[118:121]
	v_mfma_f32_16x16x32_bf16 v[114:117], v[186:189], v[194:197], v[114:117]
	v_mfma_f32_16x16x32_bf16 v[102:105], v[178:181], v[224:227], v[102:105]
	v_mfma_f32_16x16x32_bf16 v[98:101], v[186:189], v[224:227], v[98:101]
	v_mfma_f32_16x16x32_bf16 v[86:89], v[178:181], v[232:235], v[86:89]
	v_mfma_f32_16x16x32_bf16 v[82:85], v[186:189], v[232:235], v[82:85]
	v_mfma_f32_16x16x32_bf16 v[70:73], v[178:181], v[240:243], v[70:73]
	v_mfma_f32_16x16x32_bf16 v[66:69], v[186:189], v[240:243], v[66:69]
	v_mfma_f32_16x16x32_bf16 v[118:121], v[182:185], v[198:201], v[118:121]
	v_mfma_f32_16x16x32_bf16 v[114:117], v[190:193], v[198:201], v[114:117]
	v_mfma_f32_16x16x32_bf16 v[102:105], v[182:185], v[228:231], v[102:105]
	v_mfma_f32_16x16x32_bf16 v[98:101], v[190:193], v[228:231], v[98:101]
	v_mfma_f32_16x16x32_bf16 v[86:89], v[182:185], v[236:239], v[86:89]
	v_mfma_f32_16x16x32_bf16 v[82:85], v[190:193], v[236:239], v[82:85]
	v_mfma_f32_16x16x32_bf16 v[70:73], v[182:185], v[244:247], v[70:73]
	v_mfma_f32_16x16x32_bf16 v[66:69], v[190:193], v[244:247], v[66:69]
	s_setprio 0
	s_barrier
; #define PG8_STAGE(bufoff, gbase, voff) do { _Pragma("unroll") for (int _i = 0; _i < 2; ++_i) \
;         __builtin_amdgcn_global_load_lds((const unsigned*)((const char*)(gbase) + (voff)[_i]), (LAS unsigned*)(lds + (bufoff) + ldsw + _i * 8192), 16, 0, 0); } while (0)
; #define PG8_LDA(dst, b, h) do { _Pragma("unroll") for (int m = 0; m < 4; ++m) _Pragma("unroll") for (int k = 0; k < 2; ++k) dst[m][k] = *(const LAS bf16x8*)(lds + PG8_SA(b, h) + aoff + m * 2048 + k * 1024); } while (0)
; #define PG8_LDB(dst, b, h) do { _Pragma("unroll") for (int n = 0; n < 2; ++n) _Pragma("unroll") for (int k = 0; k < 2; ++k) dst[n][k] = *(const LAS bf16x8*)(lds + PG8_SB(b, h) + boff + n * 2048 + k * 1024); } while (0)
; #define PG8_MMA(ai, bj, At, Bt) do { __builtin_amdgcn_s_setprio(1); _Pragma("unroll") for (int m = 0; m < 4; ++m) _Pragma("unroll") for (int n = 0; n < 2; ++n) _Pragma("unroll") for (int k = 0; k < 2; ++k) \
;         acc[ai][bj][m][n] = __builtin_amdgcn_mfma_f32_16x16x32_bf16(Bt[n][k], At[m][k], acc[ai][bj][m][n], 0, 0, 0); __builtin_amdgcn_s_setprio(0); } while (0)
; #define PG8_WAIT_V(n) asm volatile("s_waitcnt vmcnt(" #n ")" ::: "memory")
; #define PG8_WAIT_L(n) asm volatile("s_waitcnt lgkmcnt(" #n ")" ::: "memory")
; #define PG8_BAR __builtin_amdgcn_s_barrier()
; #define PG8_SCHED __builtin_amdgcn_sched_barrier(0)
; template <class Epi, bool ALIGN_EPI = true, bool SP2 = true>
; __device__ __forceinline__ void gemm_phase(LAS unsigned char* lds, const Gemm g, const Order& S, const Epi& E) {
;     ...
;             PG8_WAIT_V(8); PG8_WAIT_L(0); PG8_BAR; PG8_MMA(0, 0, At, B0); PG8_MMA(0, 1, At, B1); PG8_BAR; PG8_SCHED;
;             PG8_LDA(At, 0, 1); PG8_STAGE(PG8_SB(0, 0), b2, voffB); PG8_STAGE(PG8_SB(0, 1), b2 + hstepB, voffB); PG8_STAGE(PG8_SA(0, 0), a2, voffA);
;             PG8_WAIT_V(8); PG8_WAIT_L(0); PG8_BAR; PG8_MMA(1, 0, At, B0); PG8_MMA(1, 1, At, B1); PG8_BAR; PG8_SCHED;
;             PG8_LDB(B0, 1, 0); PG8_LDB(B1, 1, 1); PG8_SCHED; PG8_LDA(At, 1, 0); PG8_STAGE(PG8_SA(0, 1), a2 + hstepA, voffA);
;             PG8_WAIT_V(8); PG8_WAIT_L(0); PG8_BAR; PG8_MMA(0, 0, At, B0); PG8_MMA(0, 1, At, B1); PG8_BAR; PG8_SCHED;
	s_add_i32 s65, s65, s21
	v_lshl_add_u64 v[158:159], s[70:71], 0, v[0:1]
	s_mov_b32 m0, s65
	ds_read_b128 v[194:197], v161 offset:16384
	ds_read_b128 v[198:201], v161 offset:17408
	ds_read_b128 v[224:227], v161 offset:18432
	ds_read_b128 v[228:231], v161 offset:19456
	ds_read_b128 v[232:235], v161 offset:20480
	ds_read_b128 v[236:239], v161 offset:21504
	ds_read_b128 v[240:243], v161 offset:22528
	ds_read_b128 v[244:247], v161 offset:23552
	global_load_lds_dwordx4 v[158:159], off
	s_add_i32 m0, s65, 0x2000
	s_add_u32 s66, s70, 0x40000
	v_lshl_add_u64 v[202:203], s[70:71], 0, v[134:135]
	s_addc_u32 s67, s71, 0
	s_add_i32 s57, s57, s21
	global_load_lds_dwordx4 v[202:203], off
	v_lshl_add_u64 v[210:211], s[66:67], 0, v[0:1]
	s_mov_b32 m0, s57
	v_lshl_add_u64 v[248:249], s[72:73], 0, v[132:133]
	global_load_lds_dwordx4 v[210:211], off
	v_lshl_add_u64 v[210:211], s[66:67], 0, v[134:135]
	s_add_i32 m0, s57, 0x2000
	s_nop 0
	global_load_lds_dwordx4 v[210:211], off
	v_lshl_add_u64 v[210:211], s[72:73], 0, v[130:131]
	s_mov_b32 m0, s35
	s_nop 0
	global_load_lds_dwordx4 v[210:211], off
	s_mov_b32 m0, s40
	s_nop 0
	global_load_lds_dwordx4 v[248:249], off
	s_waitcnt vmcnt(8)
	s_waitcnt lgkmcnt(0)
	s_barrier
	s_setprio 1
	s_waitcnt lgkmcnt(0)
	v_mfma_f32_16x16x32_bf16 v[62:65], v[162:165], v[194:197], v[62:65]
	v_mfma_f32_16x16x32_bf16 v[58:61], v[170:173], v[194:197], v[58:61]
	v_mfma_f32_16x16x32_bf16 v[46:49], v[162:165], v[224:227], v[46:49]
	v_mfma_f32_16x16x32_bf16 v[42:45], v[170:173], v[224:227], v[42:45]
	v_mfma_f32_16x16x32_bf16 v[30:33], v[162:165], v[232:235], v[30:33]
	v_mfma_f32_16x16x32_bf16 v[26:29], v[170:173], v[232:235], v[26:29]
	v_mfma_f32_16x16x32_bf16 v[14:17], v[162:165], v[240:243], v[14:17]
	v_mfma_f32_16x16x32_bf16 v[10:13], v[170:173], v[240:243], v[10:13]
	v_mfma_f32_16x16x32_bf16 v[62:65], v[166:169], v[198:201], v[62:65]
	v_mfma_f32_16x16x32_bf16 v[58:61], v[174:177], v[198:201], v[58:61]
	v_mfma_f32_16x16x32_bf16 v[46:49], v[166:169], v[228:231], v[46:49]
	v_mfma_f32_16x16x32_bf16 v[42:45], v[174:177], v[228:231], v[42:45]
	v_mfma_f32_16x16x32_bf16 v[30:33], v[166:169], v[236:239], v[30:33]
	v_mfma_f32_16x16x32_bf16 v[26:29], v[174:177], v[236:239], v[26:29]
	v_mfma_f32_16x16x32_bf16 v[14:17], v[166:169], v[244:247], v[14:17]
	v_mfma_f32_16x16x32_bf16 v[10:13], v[174:177], v[244:247], v[10:13]
	s_setprio 0
	s_setprio 1
	v_mfma_f32_16x16x32_bf16 v[54:57], v[178:181], v[194:197], v[54:57]
	v_mfma_f32_16x16x32_bf16 v[50:53], v[186:189], v[194:197], v[50:53]
	v_mfma_f32_16x16x32_bf16 v[38:41], v[178:181], v[224:227], v[38:41]
	v_mfma_f32_16x16x32_bf16 v[34:37], v[186:189], v[224:227], v[34:37]
	v_mfma_f32_16x16x32_bf16 v[22:25], v[178:181], v[232:235], v[22:25]
	v_mfma_f32_16x16x32_bf16 v[18:21], v[186:189], v[232:235], v[18:21]
	v_mfma_f32_16x16x32_bf16 v[6:9], v[178:181], v[240:243], v[6:9]
	v_mfma_f32_16x16x32_bf16 v[2:5], v[186:189], v[240:243], v[2:5]
	v_mfma_f32_16x16x32_bf16 v[54:57], v[182:185], v[198:201], v[54:57]
	v_mfma_f32_16x16x32_bf16 v[50:53], v[190:193], v[198:201], v[50:53]
	v_mfma_f32_16x16x32_bf16 v[38:41], v[182:185], v[228:231], v[38:41]
	v_mfma_f32_16x16x32_bf16 v[34:37], v[190:193], v[228:231], v[34:37]
	v_mfma_f32_16x16x32_bf16 v[22:25], v[182:185], v[236:239], v[22:25]
	v_mfma_f32_16x16x32_bf16 v[18:21], v[190:193], v[236:239], v[18:21]
	v_mfma_f32_16x16x32_bf16 v[6:9], v[182:185], v[244:247], v[6:9]
	v_mfma_f32_16x16x32_bf16 v[2:5], v[190:193], v[244:247], v[2:5]
	s_setprio 0
	s_barrier
	s_add_i32 s57, 0, 0x18000
	s_add_i32 s65, 0, 0x1c000
	v_add_u32_e32 v174, s57, v160
	v_add_u32_e32 v190, s65, v160
	ds_read_b128 v[162:165], v174
	ds_read_b128 v[166:169], v174 offset:1024
	ds_read_b128 v[170:173], v174 offset:2048
	ds_read_b128 v[174:177], v174 offset:3072
	ds_read_b128 v[178:181], v190
	ds_read_b128 v[182:185], v190 offset:1024
	ds_read_b128 v[186:189], v190 offset:2048
	ds_read_b128 v[190:193], v190 offset:3072
	s_add_u32 s66, s72, 0x140000
	s_addc_u32 s67, s73, 0
	s_mov_b32 m0, s42
	v_lshl_add_u64 v[250:251], s[66:67], 0, v[130:131]
	ds_read_b128 v[194:197], v161 offset:32768
	ds_read_b128 v[198:201], v161 offset:33792
	ds_read_b128 v[224:227], v161 offset:34816
	ds_read_b128 v[228:231], v161 offset:35840
	ds_read_b128 v[232:235], v161 offset:36864
	ds_read_b128 v[236:239], v161 offset:37888
	ds_read_b128 v[240:243], v161 offset:38912
	ds_read_b128 v[244:247], v161 offset:39936
	global_load_lds_dwordx4 v[250:251], off
	v_lshl_add_u64 v[250:251], s[66:67], 0, v[132:133]
	s_mov_b32 m0, s44
	s_nop 0
	global_load_lds_dwordx4 v[250:251], off
	s_waitcnt vmcnt(8)
	s_waitcnt lgkmcnt(0)
	s_barrier
; #define PG8_STAGE(bufoff, gbase, voff) do { _Pragma("unroll") for (int _i = 0; _i < 2; ++_i) \
;         __builtin_amdgcn_global_load_lds((const unsigned*)((const char*)(gbase) + (voff)[_i]), (LAS unsigned*)(lds + (bufoff) + ldsw + _i * 8192), 16, 0, 0); } while (0)
; #define PG8_LDA(dst, b, h) do { _Pragma("unroll") for (int m = 0; m < 4; ++m) _Pragma("unroll") for (int k = 0; k < 2; ++k) dst[m][k] = *(const LAS bf16x8*)(lds + PG8_SA(b, h) + aoff + m * 2048 + k * 1024); } while (0)
; #define PG8_MMA(ai, bj, At, Bt) do { __builtin_amdgcn_s_setprio(1); _Pragma("unroll") for (int m = 0; m < 4; ++m) _Pragma("unroll") for (int n = 0; n < 2; ++n) _Pragma("unroll") for (int k = 0; k < 2; ++k) \
;         acc[ai][bj][m][n] = __builtin_amdgcn_mfma_f32_16x16x32_bf16(Bt[n][k], At[m][k], acc[ai][bj][m][n], 0, 0, 0); __builtin_amdgcn_s_setprio(0); } while (0)
; #define PG8_WAIT_V(n) asm volatile("s_waitcnt vmcnt(" #n ")" ::: "memory")
; #define PG8_WAIT_L(n) asm volatile("s_waitcnt lgkmcnt(" #n ")" ::: "memory")
; #define PG8_BAR __builtin_amdgcn_s_barrier()
; #define PG8_SCHED __builtin_amdgcn_sched_barrier(0)
; template <class Epi, bool ALIGN_EPI = true, bool SP2 = true>
; __device__ __forceinline__ void gemm_phase(LAS unsigned char* lds, const Gemm g, const Order& S, const Epi& E) {
;     ...
;         for (int t = 0; t < nt; t += 2) {
;     ...
;             PG8_WAIT_V(8); PG8_WAIT_L(0); PG8_BAR; PG8_MMA(0, 0, At, B0); PG8_MMA(0, 1, At, B1); PG8_BAR; PG8_SCHED;
;             PG8_LDA(At, 1, 1); PG8_STAGE(PG8_SB(1, 0), b3, voffB); PG8_STAGE(PG8_SB(1, 1), b3 + hstepB, voffB); PG8_STAGE(PG8_SA(1, 0), a3, voffA);
;             PG8_WAIT_V(8); PG8_WAIT_L(0); PG8_BAR; PG8_MMA(1, 0, At, B0); PG8_MMA(1, 1, At, B1); PG8_BAR; PG8_SCHED;
	s_setprio 1
	s_waitcnt lgkmcnt(0)
	v_mfma_f32_16x16x32_bf16 v[126:129], v[162:165], v[194:197], v[126:129]
	v_mfma_f32_16x16x32_bf16 v[122:125], v[170:173], v[194:197], v[122:125]
	v_mfma_f32_16x16x32_bf16 v[110:113], v[162:165], v[224:227], v[110:113]
	v_mfma_f32_16x16x32_bf16 v[106:109], v[170:173], v[224:227], v[106:109]
	v_mfma_f32_16x16x32_bf16 v[94:97], v[162:165], v[232:235], v[94:97]
	v_mfma_f32_16x16x32_bf16 v[90:93], v[170:173], v[232:235], v[90:93]
	v_mfma_f32_16x16x32_bf16 v[78:81], v[162:165], v[240:243], v[78:81]
	v_mfma_f32_16x16x32_bf16 v[74:77], v[170:173], v[240:243], v[74:77]
	v_mfma_f32_16x16x32_bf16 v[126:129], v[166:169], v[198:201], v[126:129]
	v_mfma_f32_16x16x32_bf16 v[122:125], v[174:177], v[198:201], v[122:125]
	v_mfma_f32_16x16x32_bf16 v[110:113], v[166:169], v[228:231], v[110:113]
	v_mfma_f32_16x16x32_bf16 v[106:109], v[174:177], v[228:231], v[106:109]
	v_mfma_f32_16x16x32_bf16 v[94:97], v[166:169], v[236:239], v[94:97]
	v_mfma_f32_16x16x32_bf16 v[90:93], v[174:177], v[236:239], v[90:93]
	v_mfma_f32_16x16x32_bf16 v[78:81], v[166:169], v[244:247], v[78:81]
	v_mfma_f32_16x16x32_bf16 v[74:77], v[174:177], v[244:247], v[74:77]
	s_setprio 0
	s_setprio 1
	v_mfma_f32_16x16x32_bf16 v[118:121], v[178:181], v[194:197], v[118:121]
	v_mfma_f32_16x16x32_bf16 v[114:117], v[186:189], v[194:197], v[114:117]
	v_mfma_f32_16x16x32_bf16 v[102:105], v[178:181], v[224:227], v[102:105]
	v_mfma_f32_16x16x32_bf16 v[98:101], v[186:189], v[224:227], v[98:101]
	v_mfma_f32_16x16x32_bf16 v[86:89], v[178:181], v[232:235], v[86:89]
	v_mfma_f32_16x16x32_bf16 v[82:85], v[186:189], v[232:235], v[82:85]
	v_mfma_f32_16x16x32_bf16 v[70:73], v[178:181], v[240:243], v[70:73]
	v_mfma_f32_16x16x32_bf16 v[66:69], v[186:189], v[240:243], v[66:69]
	v_mfma_f32_16x16x32_bf16 v[118:121], v[182:185], v[198:201], v[118:121]
	v_mfma_f32_16x16x32_bf16 v[114:117], v[190:193], v[198:201], v[114:117]
	v_mfma_f32_16x16x32_bf16 v[102:105], v[182:185], v[228:231], v[102:105]
	v_mfma_f32_16x16x32_bf16 v[98:101], v[190:193], v[228:231], v[98:101]
	v_mfma_f32_16x16x32_bf16 v[86:89], v[182:185], v[236:239], v[86:89]
	v_mfma_f32_16x16x32_bf16 v[82:85], v[190:193], v[236:239], v[82:85]
	v_mfma_f32_16x16x32_bf16 v[70:73], v[182:185], v[244:247], v[70:73]
	v_mfma_f32_16x16x32_bf16 v[66:69], v[190:193], v[244:247], v[66:69]
	s_setprio 0
	s_barrier
	s_add_i32 s57, s57, s21
	v_lshl_add_u64 v[158:159], v[158:159], 0, s[26:27]
	s_mov_b32 m0, s57
	ds_read_b128 v[194:197], v161 offset:49152
	ds_read_b128 v[198:201], v161 offset:50176
	ds_read_b128 v[224:227], v161 offset:51200
	ds_read_b128 v[228:231], v161 offset:52224
	ds_read_b128 v[232:235], v161 offset:53248
	ds_read_b128 v[236:239], v161 offset:54272
	ds_read_b128 v[240:243], v161 offset:55296
	ds_read_b128 v[244:247], v161 offset:56320
	global_load_lds_dwordx4 v[158:159], off
	s_add_i32 m0, s57, 0x2000
	s_add_u32 s66, s70, 0x40080
	v_lshl_add_u64 v[158:159], v[202:203], 0, s[26:27]
	s_addc_u32 s67, s71, 0
	s_add_i32 s57, s65, s21
	global_load_lds_dwordx4 v[158:159], off
	v_lshl_add_u64 v[158:159], s[66:67], 0, v[0:1]
	s_mov_b32 m0, s57
	s_nop 0
	global_load_lds_dwordx4 v[158:159], off
	v_lshl_add_u64 v[158:159], s[66:67], 0, v[134:135]
	s_add_i32 m0, s57, 0x2000
	s_nop 0
	global_load_lds_dwordx4 v[158:159], off
	v_lshl_add_u64 v[158:159], v[210:211], 0, s[26:27]
	s_mov_b32 m0, s48
	s_nop 0
	global_load_lds_dwordx4 v[158:159], off
	v_lshl_add_u64 v[158:159], v[248:249], 0, s[26:27]
	s_mov_b32 m0, s49
	s_nop 0
	global_load_lds_dwordx4 v[158:159], off
	s_waitcnt vmcnt(8)
	s_waitcnt lgkmcnt(0)
	s_barrier
	s_setprio 1
	s_waitcnt lgkmcnt(0)
	v_mfma_f32_16x16x32_bf16 v[62:65], v[162:165], v[194:197], v[62:65]
	v_mfma_f32_16x16x32_bf16 v[58:61], v[170:173], v[194:197], v[58:61]
	v_mfma_f32_16x16x32_bf16 v[46:49], v[162:165], v[224:227], v[46:49]
	v_mfma_f32_16x16x32_bf16 v[42:45], v[170:173], v[224:227], v[42:45]
	v_mfma_f32_16x16x32_bf16 v[30:33], v[162:165], v[232:235], v[30:33]
	v_mfma_f32_16x16x32_bf16 v[26:29], v[170:173], v[232:235], v[26:29]
	v_mfma_f32_16x16x32_bf16 v[14:17], v[162:165], v[240:243], v[14:17]
	v_mfma_f32_16x16x32_bf16 v[10:13], v[170:173], v[240:243], v[10:13]
	v_mfma_f32_16x16x32_bf16 v[62:65], v[166:169], v[198:201], v[62:65]
	v_mfma_f32_16x16x32_bf16 v[58:61], v[174:177], v[198:201], v[58:61]
	v_mfma_f32_16x16x32_bf16 v[46:49], v[166:169], v[228:231], v[46:49]
	v_mfma_f32_16x16x32_bf16 v[42:45], v[174:177], v[228:231], v[42:45]
	v_mfma_f32_16x16x32_bf16 v[30:33], v[166:169], v[236:239], v[30:33]
	v_mfma_f32_16x16x32_bf16 v[26:29], v[174:177], v[236:239], v[26:29]
	v_mfma_f32_16x16x32_bf16 v[14:17], v[166:169], v[244:247], v[14:17]
	v_mfma_f32_16x16x32_bf16 v[10:13], v[174:177], v[244:247], v[10:13]
	s_setprio 0
	s_setprio 1
	v_mfma_f32_16x16x32_bf16 v[54:57], v[178:181], v[194:197], v[54:57]
	v_mfma_f32_16x16x32_bf16 v[50:53], v[186:189], v[194:197], v[50:53]
	v_mfma_f32_16x16x32_bf16 v[38:41], v[178:181], v[224:227], v[38:41]
	v_mfma_f32_16x16x32_bf16 v[34:37], v[186:189], v[224:227], v[34:37]
	v_mfma_f32_16x16x32_bf16 v[22:25], v[178:181], v[232:235], v[22:25]
	v_mfma_f32_16x16x32_bf16 v[18:21], v[186:189], v[232:235], v[18:21]
	v_mfma_f32_16x16x32_bf16 v[6:9], v[178:181], v[240:243], v[6:9]
	v_mfma_f32_16x16x32_bf16 v[2:5], v[186:189], v[240:243], v[2:5]
	v_mfma_f32_16x16x32_bf16 v[54:57], v[182:185], v[198:201], v[54:57]
	v_mfma_f32_16x16x32_bf16 v[50:53], v[190:193], v[198:201], v[50:53]
	v_mfma_f32_16x16x32_bf16 v[38:41], v[182:185], v[228:231], v[38:41]
	v_mfma_f32_16x16x32_bf16 v[34:37], v[190:193], v[228:231], v[34:37]
	v_mfma_f32_16x16x32_bf16 v[22:25], v[182:185], v[236:239], v[22:25]
	v_mfma_f32_16x16x32_bf16 v[18:21], v[190:193], v[236:239], v[18:21]
	v_mfma_f32_16x16x32_bf16 v[6:9], v[182:185], v[244:247], v[6:9]
	v_mfma_f32_16x16x32_bf16 v[2:5], v[190:193], v[244:247], v[2:5]
	s_setprio 0
	s_barrier
	s_add_u32 s15, s15, 0x100
	s_addc_u32 s55, s55, 0
	s_cmp_ge_i32 s63, s54
	s_mov_b64 s[66:67], s[68:69]
	s_mov_b32 s57, s63
	s_cbranch_scc0 .LBB0_724
	s_and_b64 vcc, exec, s[10:11]
	s_cbranch_vccz .LBB0_732

; #define PG8_STAGE(bufoff, gbase, voff) do { _Pragma("unroll") for (int _i = 0; _i < 2; ++_i) \
;         __builtin_amdgcn_global_load_lds((const unsigned*)((const char*)(gbase) + (voff)[_i]), (LAS unsigned*)(lds + (bufoff) + ldsw + _i * 8192), 16, 0, 0); } while (0)
; #define PG8_LDA(dst, b, h) do { _Pragma("unroll") for (int m = 0; m < 4; ++m) _Pragma("unroll") for (int k = 0; k < 2; ++k) dst[m][k] = *(const LAS bf16x8*)(lds + PG8_SA(b, h) + aoff + m * 2048 + k * 1024); } while (0)
; #define PG8_LDB(dst, b, h) do { _Pragma("unroll") for (int n = 0; n < 2; ++n) _Pragma("unroll") for (int k = 0; k < 2; ++k) dst[n][k] = *(const LAS bf16x8*)(lds + PG8_SB(b, h) + boff + n * 2048 + k * 1024); } while (0)
; #define PG8_WAIT_V(n) asm volatile("s_waitcnt vmcnt(" #n ")" ::: "memory")
; #define PG8_WAIT_L(n) asm volatile("s_waitcnt lgkmcnt(" #n ")" ::: "memory")
; #define PG8_BAR __builtin_amdgcn_s_barrier()
; #define PG8_SCHED __builtin_amdgcn_sched_barrier(0)
; template <class Epi, bool ALIGN_EPI = true, bool SP2 = true>
; __device__ __forceinline__ void gemm_phase(LAS unsigned char* lds, const Gemm g, const Order& S, const Epi& E) {
;     ...
;         const char* nA = has_next ? (const char*)(nxt.z ? g.A1 : g.A0) + (size_t)nxt.pm * tstepA + (size_t)nxt.kt0 * kstep : cA; const char* nB = has_next ? (const char*)(nxt.z ? g.B1 : g.B0) + (size_t)nxt.pn * tstepB + (size_t)nxt.kt0 * kstep : cB;
;         const int nt = cur.nkt;
;         for (int t = 0; t < nt; t += 2) {
;             const bool last = (t == nt - 2);
;             const char* a1 = cA + (size_t)(t + 1) * kstep;
;             const char* a2 = last ? nA : cA + (size_t)(t + 2) * kstep; const char* b2 = last ? nB : cB + (size_t)(t + 2) * kstep;
;             const char* a3 = a2 + kstep; const char* b3 = b2 + kstep;
;             if constexpr (SP2) {
;             PG8_LDB(B0, 0, 0); PG8_LDB(B1, 0, 1); PG8_SCHED; PG8_LDA(At, 0, 0); PG8_STAGE(PG8_SA(1, 1), a1 + hstepA, voffA);
;             PG8_WAIT_V(8); PG8_WAIT_L(0); PG8_BAR; PG8_MMA(0, 0, At, B0); PG8_MMA(0, 1, At, B1); PG8_BAR; PG8_SCHED;
;     ...
;         for (int a = 0; a < 2; ++a)
; #pragma unroll
;             for (int b = 0; b < 2; ++b)
; #pragma unroll
;                 for (int m = 0; m < 4; ++m)
; #pragma unroll
;                     for (int n = 0; n < 2; ++n) acc[a][b][m][n] = (f32x4){0.f, 0.f, 0.f, 0.f};
;         }
;         cur = nxt; cA = nA; cB = nB; ++ui;
.LBB0_879:
	s_ashr_i32 s85, s84, 31
	s_lshl_b64 s[54:55], s[84:85], 19
	s_add_u32 s11, s50, s54
	s_addc_u32 s35, s51, s55
	s_and_b64 s[54:55], s[88:89], exec
	s_cselect_b32 s87, s35, s13
	s_cselect_b32 s86, s11, s12
	s_ashr_i32 s83, s82, 31
	s_lshl_b64 s[54:55], s[82:83], 19
	s_add_u32 s11, s52, s54
	s_addc_u32 s35, s53, s55
	s_and_b64 s[54:55], s[88:89], exec
	s_cselect_b32 s89, s35, s93
	s_cselect_b32 s88, s11, s92
	s_add_u32 s12, s12, 0x40080
	s_addc_u32 s13, s13, 0
	s_add_u32 s11, s92, 0x100
	v_mov_b32_e32 v2, 0
	s_addc_u32 s35, s93, 0
	s_mov_b32 s54, -2
	v_mov_b32_e32 v3, v2
	v_mov_b32_e32 v4, v2
	v_mov_b32_e32 v5, v2
	v_mov_b32_e32 v14, v2
	v_mov_b32_e32 v15, v2
	v_mov_b32_e32 v16, v2
	v_mov_b32_e32 v17, v2
	v_mov_b32_e32 v18, v2
	v_mov_b32_e32 v19, v2
	v_mov_b32_e32 v20, v2
	v_mov_b32_e32 v21, v2
	v_mov_b32_e32 v30, v2
	v_mov_b32_e32 v31, v2
	v_mov_b32_e32 v32, v2
	v_mov_b32_e32 v33, v2
	v_mov_b32_e32 v34, v2
	v_mov_b32_e32 v35, v2
	v_mov_b32_e32 v36, v2
	v_mov_b32_e32 v37, v2
	v_mov_b32_e32 v46, v2
	v_mov_b32_e32 v47, v2
	v_mov_b32_e32 v48, v2
	v_mov_b32_e32 v49, v2
	v_mov_b32_e32 v82, v2
	v_mov_b32_e32 v83, v2
	v_mov_b32_e32 v84, v2
	v_mov_b32_e32 v85, v2
	v_mov_b32_e32 v94, v2
	v_mov_b32_e32 v95, v2
	v_mov_b32_e32 v96, v2
	v_mov_b32_e32 v97, v2
	v_mov_b32_e32 v6, v2
	v_mov_b32_e32 v7, v2
	v_mov_b32_e32 v8, v2
	v_mov_b32_e32 v9, v2
	v_mov_b32_e32 v10, v2
	v_mov_b32_e32 v11, v2
	v_mov_b32_e32 v12, v2
	v_mov_b32_e32 v13, v2
	v_mov_b32_e32 v22, v2
	v_mov_b32_e32 v23, v2
	v_mov_b32_e32 v24, v2
	v_mov_b32_e32 v25, v2
	v_mov_b32_e32 v26, v2
	v_mov_b32_e32 v27, v2
	v_mov_b32_e32 v28, v2
	v_mov_b32_e32 v29, v2
	v_mov_b32_e32 v38, v2
	v_mov_b32_e32 v39, v2
	v_mov_b32_e32 v40, v2
	v_mov_b32_e32 v41, v2
	v_mov_b32_e32 v42, v2
	v_mov_b32_e32 v43, v2
	v_mov_b32_e32 v44, v2
	v_mov_b32_e32 v45, v2
	v_mov_b32_e32 v86, v2
	v_mov_b32_e32 v87, v2
	v_mov_b32_e32 v88, v2
	v_mov_b32_e32 v89, v2
	v_mov_b32_e32 v90, v2
	v_mov_b32_e32 v91, v2
	v_mov_b32_e32 v92, v2
	v_mov_b32_e32 v93, v2
	v_mov_b32_e32 v106, v2
	v_mov_b32_e32 v107, v2
	v_mov_b32_e32 v108, v2
	v_mov_b32_e32 v109, v2
	v_mov_b32_e32 v114, v2
	v_mov_b32_e32 v115, v2
	v_mov_b32_e32 v116, v2
	v_mov_b32_e32 v117, v2
	v_mov_b32_e32 v122, v2
	v_mov_b32_e32 v123, v2
	v_mov_b32_e32 v124, v2
	v_mov_b32_e32 v125, v2
	v_mov_b32_e32 v130, v2
	v_mov_b32_e32 v131, v2
	v_mov_b32_e32 v132, v2
	v_mov_b32_e32 v133, v2
	v_mov_b32_e32 v138, v2
	v_mov_b32_e32 v139, v2
	v_mov_b32_e32 v140, v2
	v_mov_b32_e32 v141, v2
	v_mov_b32_e32 v146, v2
	v_mov_b32_e32 v147, v2
	v_mov_b32_e32 v148, v2
	v_mov_b32_e32 v149, v2
	v_mov_b32_e32 v154, v2
	v_mov_b32_e32 v155, v2
	v_mov_b32_e32 v156, v2
	v_mov_b32_e32 v157, v2
	v_mov_b32_e32 v158, v2
	v_mov_b32_e32 v159, v2
	v_mov_b32_e32 v160, v2
	v_mov_b32_e32 v161, v2
	v_mov_b32_e32 v98, v2
	v_mov_b32_e32 v99, v2
	v_mov_b32_e32 v100, v2
	v_mov_b32_e32 v101, v2
	v_mov_b32_e32 v102, v2
	v_mov_b32_e32 v103, v2
	v_mov_b32_e32 v104, v2
	v_mov_b32_e32 v105, v2
	v_mov_b32_e32 v110, v2
	v_mov_b32_e32 v111, v2
	v_mov_b32_e32 v112, v2
	v_mov_b32_e32 v113, v2
	v_mov_b32_e32 v118, v2
	v_mov_b32_e32 v119, v2
	v_mov_b32_e32 v120, v2
	v_mov_b32_e32 v121, v2
	v_mov_b32_e32 v126, v2
	v_mov_b32_e32 v127, v2
	v_mov_b32_e32 v128, v2
	v_mov_b32_e32 v129, v2
	v_mov_b32_e32 v134, v2
	v_mov_b32_e32 v135, v2
	v_mov_b32_e32 v136, v2
	v_mov_b32_e32 v137, v2
	v_mov_b32_e32 v142, v2
	v_mov_b32_e32 v143, v2
	v_mov_b32_e32 v144, v2
	v_mov_b32_e32 v145, v2
	v_mov_b32_e32 v150, v2
	v_mov_b32_e32 v151, v2
	v_mov_b32_e32 v152, v2
	v_mov_b32_e32 v153, v2
	.p2align	6
.LBB0_880:
	s_add_u32 s55, s12, 0xfffc0080
	s_addc_u32 s83, s13, -1
	s_add_i32 s85, 0, 0x10000
	s_cmp_eq_u32 s54, 12
	s_cselect_b32 s95, s87, s83
	s_cselect_b32 s94, s86, s55
	v_add_u32_e32 v0, s85, v179
	s_cselect_b32 s93, s89, s35
	s_cselect_b32 s92, s88, s11
	s_add_i32 s55, 0, 0x14000
	ds_read_b128 v[50:53], v0
	ds_read_b128 v[54:57], v0 offset:1024
	ds_read_b128 v[58:61], v0 offset:2048
	ds_read_b128 v[62:65], v0 offset:3072
	v_add_u32_e32 v0, s55, v179
	ds_read_b128 v[66:69], v0
	ds_read_b128 v[70:73], v0 offset:1024
	ds_read_b128 v[74:77], v0 offset:2048
	ds_read_b128 v[78:81], v0 offset:3072
	v_lshl_add_u64 v[210:211], s[12:13], 0, v[170:171]
	s_add_i32 m0, s46, 0xc000
	ds_read_b128 v[174:177], v182
	ds_read_b128 v[184:187], v182 offset:1024
	ds_read_b128 v[188:191], v182 offset:2048
	ds_read_b128 v[192:195], v182 offset:3072
	ds_read_b128 v[196:199], v182 offset:4096
	ds_read_b128 v[200:203], v182 offset:5120
	ds_read_b128 v[224:227], v182 offset:6144
	ds_read_b128 v[228:231], v182 offset:7168
	global_load_lds_dwordx4 v[210:211], off
	v_lshl_add_u64 v[210:211], s[12:13], 0, v[172:173]
	s_add_i32 m0, s46, 0xe000
	s_nop 0
	global_load_lds_dwordx4 v[210:211], off
	s_waitcnt vmcnt(8)
	s_waitcnt lgkmcnt(0)
	s_barrier
; #define PG8_STAGE(bufoff, gbase, voff) do { _Pragma("unroll") for (int _i = 0; _i < 2; ++_i) \
;         __builtin_amdgcn_global_load_lds((const unsigned*)((const char*)(gbase) + (voff)[_i]), (LAS unsigned*)(lds + (bufoff) + ldsw + _i * 8192), 16, 0, 0); } while (0)
; #define PG8_LDA(dst, b, h) do { _Pragma("unroll") for (int m = 0; m < 4; ++m) _Pragma("unroll") for (int k = 0; k < 2; ++k) dst[m][k] = *(const LAS bf16x8*)(lds + PG8_SA(b, h) + aoff + m * 2048 + k * 1024); } while (0)
; #define PG8_MMA(ai, bj, At, Bt) do { __builtin_amdgcn_s_setprio(1); _Pragma("unroll") for (int m = 0; m < 4; ++m) _Pragma("unroll") for (int n = 0; n < 2; ++n) _Pragma("unroll") for (int k = 0; k < 2; ++k) \
;         acc[ai][bj][m][n] = __builtin_amdgcn_mfma_f32_16x16x32_bf16(Bt[n][k], At[m][k], acc[ai][bj][m][n], 0, 0, 0); __builtin_amdgcn_s_setprio(0); } while (0)
; #define PG8_WAIT_V(n) asm volatile("s_waitcnt vmcnt(" #n ")" ::: "memory")
; #define PG8_WAIT_L(n) asm volatile("s_waitcnt lgkmcnt(" #n ")" ::: "memory")
; #define PG8_BAR __builtin_amdgcn_s_barrier()
; #define PG8_SCHED __builtin_amdgcn_sched_barrier(0)
; template <class Epi, bool ALIGN_EPI = true, bool SP2 = true>
; __device__ __forceinline__ void gemm_phase(LAS unsigned char* lds, const Gemm g, const Order& S, const Epi& E) {
;     ...
;             PG8_WAIT_V(8); PG8_WAIT_L(0); PG8_BAR; PG8_MMA(0, 0, At, B0); PG8_MMA(0, 1, At, B1); PG8_BAR; PG8_SCHED;
;             PG8_LDA(At, 0, 1); PG8_STAGE(PG8_SB(0, 0), b2, voffB); PG8_STAGE(PG8_SB(0, 1), b2 + hstepB, voffB); PG8_STAGE(PG8_SA(0, 0), a2, voffA);
;             PG8_WAIT_V(8); PG8_WAIT_L(0); PG8_BAR; PG8_MMA(1, 0, At, B0); PG8_MMA(1, 1, At, B1); PG8_BAR; PG8_SCHED;
	s_setprio 1
	s_waitcnt lgkmcnt(0)
	v_mfma_f32_16x16x32_bf16 v[150:153], v[50:53], v[174:177], v[150:153]
	v_mfma_f32_16x16x32_bf16 v[142:145], v[58:61], v[174:177], v[142:145]
	v_mfma_f32_16x16x32_bf16 v[134:137], v[50:53], v[188:191], v[134:137]
	v_mfma_f32_16x16x32_bf16 v[126:129], v[58:61], v[188:191], v[126:129]
	v_mfma_f32_16x16x32_bf16 v[118:121], v[50:53], v[196:199], v[118:121]
	v_mfma_f32_16x16x32_bf16 v[110:113], v[58:61], v[196:199], v[110:113]
	v_mfma_f32_16x16x32_bf16 v[102:105], v[50:53], v[224:227], v[102:105]
	v_mfma_f32_16x16x32_bf16 v[98:101], v[58:61], v[224:227], v[98:101]
	v_mfma_f32_16x16x32_bf16 v[150:153], v[54:57], v[184:187], v[150:153]
	v_mfma_f32_16x16x32_bf16 v[142:145], v[62:65], v[184:187], v[142:145]
	v_mfma_f32_16x16x32_bf16 v[134:137], v[54:57], v[192:195], v[134:137]
	v_mfma_f32_16x16x32_bf16 v[126:129], v[62:65], v[192:195], v[126:129]
	v_mfma_f32_16x16x32_bf16 v[118:121], v[54:57], v[200:203], v[118:121]
	v_mfma_f32_16x16x32_bf16 v[110:113], v[62:65], v[200:203], v[110:113]
	v_mfma_f32_16x16x32_bf16 v[102:105], v[54:57], v[228:231], v[102:105]
	v_mfma_f32_16x16x32_bf16 v[98:101], v[62:65], v[228:231], v[98:101]
	s_setprio 0
	s_setprio 1
	v_mfma_f32_16x16x32_bf16 v[158:161], v[66:69], v[174:177], v[158:161]
	v_mfma_f32_16x16x32_bf16 v[154:157], v[74:77], v[174:177], v[154:157]
	v_mfma_f32_16x16x32_bf16 v[146:149], v[66:69], v[188:191], v[146:149]
	v_mfma_f32_16x16x32_bf16 v[138:141], v[74:77], v[188:191], v[138:141]
	v_mfma_f32_16x16x32_bf16 v[130:133], v[66:69], v[196:199], v[130:133]
	v_mfma_f32_16x16x32_bf16 v[122:125], v[74:77], v[196:199], v[122:125]
	v_mfma_f32_16x16x32_bf16 v[114:117], v[66:69], v[224:227], v[114:117]
	v_mfma_f32_16x16x32_bf16 v[106:109], v[74:77], v[224:227], v[106:109]
	v_mfma_f32_16x16x32_bf16 v[158:161], v[70:73], v[184:187], v[158:161]
	v_mfma_f32_16x16x32_bf16 v[154:157], v[78:81], v[184:187], v[154:157]
	v_mfma_f32_16x16x32_bf16 v[146:149], v[70:73], v[192:195], v[146:149]
	v_mfma_f32_16x16x32_bf16 v[138:141], v[78:81], v[192:195], v[138:141]
	v_mfma_f32_16x16x32_bf16 v[130:133], v[70:73], v[200:203], v[130:133]
	v_mfma_f32_16x16x32_bf16 v[122:125], v[78:81], v[200:203], v[122:125]
	v_mfma_f32_16x16x32_bf16 v[114:117], v[70:73], v[228:231], v[114:117]
	v_mfma_f32_16x16x32_bf16 v[106:109], v[78:81], v[228:231], v[106:109]
	s_setprio 0
	s_barrier
	s_add_i32 s83, s85, s49
	v_lshl_add_u64 v[210:211], s[92:93], 0, v[164:165]
	s_mov_b32 m0, s83
	ds_read_b128 v[174:177], v182 offset:16384
	ds_read_b128 v[184:187], v182 offset:17408
	ds_read_b128 v[188:191], v182 offset:18432
	ds_read_b128 v[192:195], v182 offset:19456
	ds_read_b128 v[196:199], v182 offset:20480
	ds_read_b128 v[200:203], v182 offset:21504
	ds_read_b128 v[224:227], v182 offset:22528
	ds_read_b128 v[228:231], v182 offset:23552
	global_load_lds_dwordx4 v[210:211], off
	s_add_i32 m0, s83, 0x2000
	s_add_u32 vcc_lo, s92, 0x40000
	v_lshl_add_u64 v[236:237], s[92:93], 0, v[168:169]
	s_addc_u32 vcc_hi, s93, 0
	s_add_i32 s55, s55, s49
	global_load_lds_dwordx4 v[236:237], off
	v_lshl_add_u64 v[232:233], vcc, 0, v[164:165]
	s_mov_b32 m0, s55
	v_lshl_add_u64 v[238:239], s[94:95], 0, v[162:163]
	global_load_lds_dwordx4 v[232:233], off
	v_lshl_add_u64 v[232:233], vcc, 0, v[168:169]
	s_add_i32 m0, s55, 0x2000
	v_lshl_add_u64 v[240:241], s[94:95], 0, v[166:167]
	global_load_lds_dwordx4 v[232:233], off
	s_mov_b32 m0, s46
	s_nop 0
	global_load_lds_dwordx4 v[238:239], off
	s_mov_b32 m0, s40
	s_nop 0
	global_load_lds_dwordx4 v[240:241], off
	s_waitcnt vmcnt(8)
	s_waitcnt lgkmcnt(0)
	s_barrier
	s_setprio 1
	s_waitcnt lgkmcnt(0)
	v_mfma_f32_16x16x32_bf16 v[90:93], v[50:53], v[174:177], v[90:93]
	v_mfma_f32_16x16x32_bf16 v[86:89], v[58:61], v[174:177], v[86:89]
	v_mfma_f32_16x16x32_bf16 v[42:45], v[50:53], v[188:191], v[42:45]
	v_mfma_f32_16x16x32_bf16 v[38:41], v[58:61], v[188:191], v[38:41]
	v_mfma_f32_16x16x32_bf16 v[26:29], v[50:53], v[196:199], v[26:29]
	v_mfma_f32_16x16x32_bf16 v[22:25], v[58:61], v[196:199], v[22:25]
	v_mfma_f32_16x16x32_bf16 v[10:13], v[50:53], v[224:227], v[10:13]
	v_mfma_f32_16x16x32_bf16 v[6:9], v[58:61], v[224:227], v[6:9]
	v_mfma_f32_16x16x32_bf16 v[90:93], v[54:57], v[184:187], v[90:93]
	v_mfma_f32_16x16x32_bf16 v[86:89], v[62:65], v[184:187], v[86:89]
	v_mfma_f32_16x16x32_bf16 v[42:45], v[54:57], v[192:195], v[42:45]
	v_mfma_f32_16x16x32_bf16 v[38:41], v[62:65], v[192:195], v[38:41]
	v_mfma_f32_16x16x32_bf16 v[26:29], v[54:57], v[200:203], v[26:29]
	v_mfma_f32_16x16x32_bf16 v[22:25], v[62:65], v[200:203], v[22:25]
	v_mfma_f32_16x16x32_bf16 v[10:13], v[54:57], v[228:231], v[10:13]
	v_mfma_f32_16x16x32_bf16 v[6:9], v[62:65], v[228:231], v[6:9]
	s_setprio 0
	s_setprio 1
	v_mfma_f32_16x16x32_bf16 v[46:49], v[66:69], v[188:191], v[46:49]
	v_mfma_f32_16x16x32_bf16 v[34:37], v[74:77], v[188:191], v[34:37]
	v_mfma_f32_16x16x32_bf16 v[30:33], v[66:69], v[196:199], v[30:33]
	v_mfma_f32_16x16x32_bf16 v[18:21], v[74:77], v[196:199], v[18:21]
	v_mfma_f32_16x16x32_bf16 v[14:17], v[66:69], v[224:227], v[14:17]
	v_mfma_f32_16x16x32_bf16 v[2:5], v[74:77], v[224:227], v[2:5]
	v_mfma_f32_16x16x32_bf16 v[50:53], v[66:69], v[174:177], v[94:97]
	v_mfma_f32_16x16x32_bf16 v[54:57], v[74:77], v[174:177], v[82:85]
	v_mfma_f32_16x16x32_bf16 v[46:49], v[70:73], v[192:195], v[46:49]
	v_mfma_f32_16x16x32_bf16 v[34:37], v[78:81], v[192:195], v[34:37]
	v_mfma_f32_16x16x32_bf16 v[30:33], v[70:73], v[200:203], v[30:33]
	v_mfma_f32_16x16x32_bf16 v[18:21], v[78:81], v[200:203], v[18:21]
	v_mfma_f32_16x16x32_bf16 v[14:17], v[70:73], v[228:231], v[14:17]
	v_mfma_f32_16x16x32_bf16 v[2:5], v[78:81], v[228:231], v[2:5]
	v_mfma_f32_16x16x32_bf16 v[50:53], v[70:73], v[184:187], v[50:53]
	v_mfma_f32_16x16x32_bf16 v[54:57], v[78:81], v[184:187], v[54:57]
	s_setprio 0
	s_barrier
; #define PG8_STAGE(bufoff, gbase, voff) do { _Pragma("unroll") for (int _i = 0; _i < 2; ++_i) \
;         __builtin_amdgcn_global_load_lds((const unsigned*)((const char*)(gbase) + (voff)[_i]), (LAS unsigned*)(lds + (bufoff) + ldsw + _i * 8192), 16, 0, 0); } while (0)
; #define PG8_LDA(dst, b, h) do { _Pragma("unroll") for (int m = 0; m < 4; ++m) _Pragma("unroll") for (int k = 0; k < 2; ++k) dst[m][k] = *(const LAS bf16x8*)(lds + PG8_SA(b, h) + aoff + m * 2048 + k * 1024); } while (0)
; #define PG8_LDB(dst, b, h) do { _Pragma("unroll") for (int n = 0; n < 2; ++n) _Pragma("unroll") for (int k = 0; k < 2; ++k) dst[n][k] = *(const LAS bf16x8*)(lds + PG8_SB(b, h) + boff + n * 2048 + k * 1024); } while (0)
; #define PG8_MMA(ai, bj, At, Bt) do { __builtin_amdgcn_s_setprio(1); _Pragma("unroll") for (int m = 0; m < 4; ++m) _Pragma("unroll") for (int n = 0; n < 2; ++n) _Pragma("unroll") for (int k = 0; k < 2; ++k) \
;         acc[ai][bj][m][n] = __builtin_amdgcn_mfma_f32_16x16x32_bf16(Bt[n][k], At[m][k], acc[ai][bj][m][n], 0, 0, 0); __builtin_amdgcn_s_setprio(0); } while (0)
; #define PG8_WAIT_V(n) asm volatile("s_waitcnt vmcnt(" #n ")" ::: "memory")
; #define PG8_WAIT_L(n) asm volatile("s_waitcnt lgkmcnt(" #n ")" ::: "memory")
; #define PG8_BAR __builtin_amdgcn_s_barrier()
; #define PG8_SCHED __builtin_amdgcn_sched_barrier(0)
; template <class Epi, bool ALIGN_EPI = true, bool SP2 = true>
; __device__ __forceinline__ void gemm_phase(LAS unsigned char* lds, const Gemm g, const Order& S, const Epi& E) {
;     ...
;             PG8_LDB(B0, 1, 0); PG8_LDB(B1, 1, 1); PG8_SCHED; PG8_LDA(At, 1, 0); PG8_STAGE(PG8_SA(0, 1), a2 + hstepA, voffA);
;             PG8_WAIT_V(8); PG8_WAIT_L(0); PG8_BAR; PG8_MMA(0, 0, At, B0); PG8_MMA(0, 1, At, B1); PG8_BAR; PG8_SCHED;
	s_add_i32 s55, 0, 0x18000
	v_add_u32_e32 v0, s55, v179
	s_add_i32 s83, 0, 0x1c000
	ds_read_b128 v[58:61], v0
	ds_read_b128 v[62:65], v0 offset:1024
	ds_read_b128 v[66:69], v0 offset:2048
	ds_read_b128 v[70:73], v0 offset:3072
	v_add_u32_e32 v0, s83, v179
	ds_read_b128 v[74:77], v0
	ds_read_b128 v[78:81], v0 offset:1024
	ds_read_b128 v[174:177], v0 offset:2048
	ds_read_b128 v[184:187], v0 offset:3072
	s_add_u32 s94, s94, 0x40000
	s_addc_u32 s95, s95, 0
	s_mov_b32 m0, s42
	v_lshl_add_u64 v[232:233], s[94:95], 0, v[162:163]
	ds_read_b128 v[82:85], v182 offset:32768
	ds_read_b128 v[94:97], v182 offset:33792
	ds_read_b128 v[188:191], v182 offset:34816
	ds_read_b128 v[192:195], v182 offset:35840
	ds_read_b128 v[196:199], v182 offset:36864
	ds_read_b128 v[200:203], v182 offset:37888
	ds_read_b128 v[224:227], v182 offset:38912
	ds_read_b128 v[228:231], v182 offset:39936
	global_load_lds_dwordx4 v[232:233], off
	v_lshl_add_u64 v[232:233], s[94:95], 0, v[166:167]
	s_mov_b32 m0, s44
	s_nop 0
	global_load_lds_dwordx4 v[232:233], off
	s_waitcnt vmcnt(8)
	s_waitcnt lgkmcnt(0)
	s_barrier
	s_setprio 1
	s_waitcnt lgkmcnt(0)
	v_mfma_f32_16x16x32_bf16 v[150:153], v[58:61], v[82:85], v[150:153]
	v_mfma_f32_16x16x32_bf16 v[142:145], v[66:69], v[82:85], v[142:145]
	v_mfma_f32_16x16x32_bf16 v[134:137], v[58:61], v[188:191], v[134:137]
	v_mfma_f32_16x16x32_bf16 v[126:129], v[66:69], v[188:191], v[126:129]
	v_mfma_f32_16x16x32_bf16 v[118:121], v[58:61], v[196:199], v[118:121]
	v_mfma_f32_16x16x32_bf16 v[110:113], v[66:69], v[196:199], v[110:113]
	v_mfma_f32_16x16x32_bf16 v[102:105], v[58:61], v[224:227], v[102:105]
	v_mfma_f32_16x16x32_bf16 v[98:101], v[66:69], v[224:227], v[98:101]
	v_mfma_f32_16x16x32_bf16 v[150:153], v[62:65], v[94:97], v[150:153]
	v_mfma_f32_16x16x32_bf16 v[142:145], v[70:73], v[94:97], v[142:145]
	v_mfma_f32_16x16x32_bf16 v[134:137], v[62:65], v[192:195], v[134:137]
	v_mfma_f32_16x16x32_bf16 v[126:129], v[70:73], v[192:195], v[126:129]
	v_mfma_f32_16x16x32_bf16 v[118:121], v[62:65], v[200:203], v[118:121]
	v_mfma_f32_16x16x32_bf16 v[110:113], v[70:73], v[200:203], v[110:113]
	v_mfma_f32_16x16x32_bf16 v[102:105], v[62:65], v[228:231], v[102:105]
	v_mfma_f32_16x16x32_bf16 v[98:101], v[70:73], v[228:231], v[98:101]
	s_setprio 0
	s_setprio 1
	v_mfma_f32_16x16x32_bf16 v[158:161], v[74:77], v[82:85], v[158:161]
	v_mfma_f32_16x16x32_bf16 v[82:85], v[174:177], v[82:85], v[154:157]
	v_mfma_f32_16x16x32_bf16 v[154:157], v[184:187], v[94:97], v[82:85]
	v_mfma_f32_16x16x32_bf16 v[82:85], v[74:77], v[188:191], v[146:149]
	v_mfma_f32_16x16x32_bf16 v[146:149], v[78:81], v[192:195], v[82:85]
	v_mfma_f32_16x16x32_bf16 v[82:85], v[174:177], v[188:191], v[138:141]
	v_mfma_f32_16x16x32_bf16 v[138:141], v[184:187], v[192:195], v[82:85]
	v_mfma_f32_16x16x32_bf16 v[82:85], v[74:77], v[196:199], v[130:133]
	v_mfma_f32_16x16x32_bf16 v[130:133], v[78:81], v[200:203], v[82:85]
	v_mfma_f32_16x16x32_bf16 v[82:85], v[174:177], v[196:199], v[122:125]
	v_mfma_f32_16x16x32_bf16 v[122:125], v[184:187], v[200:203], v[82:85]
	v_mfma_f32_16x16x32_bf16 v[82:85], v[74:77], v[224:227], v[114:117]
	v_mfma_f32_16x16x32_bf16 v[114:117], v[78:81], v[228:231], v[82:85]
	v_mfma_f32_16x16x32_bf16 v[82:85], v[174:177], v[224:227], v[106:109]
	v_mfma_f32_16x16x32_bf16 v[158:161], v[78:81], v[94:97], v[158:161]
	v_mfma_f32_16x16x32_bf16 v[106:109], v[184:187], v[228:231], v[82:85]
	s_setprio 0
	s_barrier
; #define PG8_STAGE(bufoff, gbase, voff) do { _Pragma("unroll") for (int _i = 0; _i < 2; ++_i) \
;         __builtin_amdgcn_global_load_lds((const unsigned*)((const char*)(gbase) + (voff)[_i]), (LAS unsigned*)(lds + (bufoff) + ldsw + _i * 8192), 16, 0, 0); } while (0)
; #define PG8_LDA(dst, b, h) do { _Pragma("unroll") for (int m = 0; m < 4; ++m) _Pragma("unroll") for (int k = 0; k < 2; ++k) dst[m][k] = *(const LAS bf16x8*)(lds + PG8_SA(b, h) + aoff + m * 2048 + k * 1024); } while (0)
; #define PG8_MMA(ai, bj, At, Bt) do { __builtin_amdgcn_s_setprio(1); _Pragma("unroll") for (int m = 0; m < 4; ++m) _Pragma("unroll") for (int n = 0; n < 2; ++n) _Pragma("unroll") for (int k = 0; k < 2; ++k) \
;         acc[ai][bj][m][n] = __builtin_amdgcn_mfma_f32_16x16x32_bf16(Bt[n][k], At[m][k], acc[ai][bj][m][n], 0, 0, 0); __builtin_amdgcn_s_setprio(0); } while (0)
; #define PG8_WAIT_V(n) asm volatile("s_waitcnt vmcnt(" #n ")" ::: "memory")
; #define PG8_WAIT_L(n) asm volatile("s_waitcnt lgkmcnt(" #n ")" ::: "memory")
; #define PG8_BAR __builtin_amdgcn_s_barrier()
; #define PG8_SCHED __builtin_amdgcn_sched_barrier(0)
; template <class Epi, bool ALIGN_EPI = true, bool SP2 = true>
; __device__ __forceinline__ void gemm_phase(LAS unsigned char* lds, const Gemm g, const Order& S, const Epi& E) {
;     ...
;         for (int t = 0; t < nt; t += 2) {
;     ...
;             PG8_LDA(At, 1, 1); PG8_STAGE(PG8_SB(1, 0), b3, voffB); PG8_STAGE(PG8_SB(1, 1), b3 + hstepB, voffB); PG8_STAGE(PG8_SA(1, 0), a3, voffA);
;             PG8_WAIT_V(8); PG8_WAIT_L(0); PG8_BAR; PG8_MMA(1, 0, At, B0); PG8_MMA(1, 1, At, B1); PG8_BAR; PG8_SCHED;
	s_add_i32 s55, s55, s49
	v_lshl_add_u64 v[94:95], v[210:211], 0, s[26:27]
	s_mov_b32 m0, s55
	s_nop 0
	ds_read_b128 v[82:85], v182 offset:49152
	ds_read_b128 v[188:191], v182 offset:50176
	ds_read_b128 v[192:195], v182 offset:51200
	ds_read_b128 v[196:199], v182 offset:52224
	ds_read_b128 v[200:203], v182 offset:53248
	ds_read_b128 v[224:227], v182 offset:54272
	ds_read_b128 v[228:231], v182 offset:55296
	ds_read_b128 v[232:235], v182 offset:56320
	global_load_lds_dwordx4 v[94:95], off
	s_add_i32 m0, s55, 0x2000
	s_add_u32 s92, s92, 0x40080
	v_lshl_add_u64 v[94:95], v[236:237], 0, s[26:27]
	s_addc_u32 s93, s93, 0
	s_add_i32 s55, s83, s49
	global_load_lds_dwordx4 v[94:95], off
	v_lshl_add_u64 v[94:95], s[92:93], 0, v[164:165]
	s_mov_b32 m0, s55
	s_nop 0
	global_load_lds_dwordx4 v[94:95], off
	v_lshl_add_u64 v[94:95], s[92:93], 0, v[168:169]
	s_add_i32 m0, s55, 0x2000
	s_nop 0
	global_load_lds_dwordx4 v[94:95], off
	v_lshl_add_u64 v[94:95], v[238:239], 0, s[26:27]
	s_mov_b32 m0, s19
	s_nop 0
	global_load_lds_dwordx4 v[94:95], off
	v_lshl_add_u64 v[94:95], v[240:241], 0, s[26:27]
	s_mov_b32 m0, s45
	s_nop 0
	global_load_lds_dwordx4 v[94:95], off
	s_waitcnt vmcnt(8)
	s_waitcnt lgkmcnt(0)
	s_barrier
	s_setprio 1
	s_waitcnt lgkmcnt(0)
	v_mfma_f32_16x16x32_bf16 v[90:93], v[58:61], v[82:85], v[90:93]
	v_mfma_f32_16x16x32_bf16 v[86:89], v[66:69], v[82:85], v[86:89]
	v_mfma_f32_16x16x32_bf16 v[42:45], v[58:61], v[192:195], v[42:45]
	v_mfma_f32_16x16x32_bf16 v[38:41], v[66:69], v[192:195], v[38:41]
	v_mfma_f32_16x16x32_bf16 v[26:29], v[58:61], v[200:203], v[26:29]
	v_mfma_f32_16x16x32_bf16 v[22:25], v[66:69], v[200:203], v[22:25]
	v_mfma_f32_16x16x32_bf16 v[10:13], v[58:61], v[228:231], v[10:13]
	v_mfma_f32_16x16x32_bf16 v[6:9], v[66:69], v[228:231], v[6:9]
	v_mfma_f32_16x16x32_bf16 v[90:93], v[62:65], v[188:191], v[90:93]
	v_mfma_f32_16x16x32_bf16 v[86:89], v[70:73], v[188:191], v[86:89]
	v_mfma_f32_16x16x32_bf16 v[42:45], v[62:65], v[196:199], v[42:45]
	v_mfma_f32_16x16x32_bf16 v[38:41], v[70:73], v[196:199], v[38:41]
	v_mfma_f32_16x16x32_bf16 v[26:29], v[62:65], v[224:227], v[26:29]
	v_mfma_f32_16x16x32_bf16 v[22:25], v[70:73], v[224:227], v[22:25]
	v_mfma_f32_16x16x32_bf16 v[10:13], v[62:65], v[232:235], v[10:13]
	v_mfma_f32_16x16x32_bf16 v[6:9], v[70:73], v[232:235], v[6:9]
	s_setprio 0
	s_setprio 1
	v_mfma_f32_16x16x32_bf16 v[50:53], v[74:77], v[82:85], v[50:53]
	v_mfma_f32_16x16x32_bf16 v[94:97], v[78:81], v[188:191], v[50:53]
	v_mfma_f32_16x16x32_bf16 v[50:53], v[174:177], v[82:85], v[54:57]
	v_mfma_f32_16x16x32_bf16 v[46:49], v[74:77], v[192:195], v[46:49]
	v_mfma_f32_16x16x32_bf16 v[34:37], v[174:177], v[192:195], v[34:37]
	v_mfma_f32_16x16x32_bf16 v[30:33], v[74:77], v[200:203], v[30:33]
	v_mfma_f32_16x16x32_bf16 v[18:21], v[174:177], v[200:203], v[18:21]
	v_mfma_f32_16x16x32_bf16 v[14:17], v[74:77], v[228:231], v[14:17]
	v_mfma_f32_16x16x32_bf16 v[2:5], v[174:177], v[228:231], v[2:5]
	v_mfma_f32_16x16x32_bf16 v[82:85], v[184:187], v[188:191], v[50:53]
	v_mfma_f32_16x16x32_bf16 v[46:49], v[78:81], v[196:199], v[46:49]
	v_mfma_f32_16x16x32_bf16 v[34:37], v[184:187], v[196:199], v[34:37]
	v_mfma_f32_16x16x32_bf16 v[30:33], v[78:81], v[224:227], v[30:33]
	v_mfma_f32_16x16x32_bf16 v[18:21], v[184:187], v[224:227], v[18:21]
	v_mfma_f32_16x16x32_bf16 v[14:17], v[78:81], v[232:235], v[14:17]
	v_mfma_f32_16x16x32_bf16 v[2:5], v[184:187], v[232:235], v[2:5]
	s_setprio 0
	s_barrier
	s_add_i32 s54, s54, 2
	s_add_u32 s12, s12, 0x100
	s_addc_u32 s13, s13, 0
	s_add_u32 s11, s11, 0x100
	s_addc_u32 s35, s35, 0
	s_cmp_gt_u32 s54, 13
	s_cbranch_scc0 .LBB0_880
	s_and_b64 vcc, exec, s[76:77]
	s_cbranch_vccz .LBB0_883
	s_barrier

; #define PG8_STAGE(bufoff, gbase, voff) do { _Pragma("unroll") for (int _i = 0; _i < 2; ++_i) \
;         __builtin_amdgcn_global_load_lds((const unsigned*)((const char*)(gbase) + (voff)[_i]), (LAS unsigned*)(lds + (bufoff) + ldsw + _i * 8192), 16, 0, 0); } while (0)
; #define PG8_LDA(dst, b, h) do { _Pragma("unroll") for (int m = 0; m < 4; ++m) _Pragma("unroll") for (int k = 0; k < 2; ++k) dst[m][k] = *(const LAS bf16x8*)(lds + PG8_SA(b, h) + aoff + m * 2048 + k * 1024); } while (0)
; #define PG8_LDB(dst, b, h) do { _Pragma("unroll") for (int n = 0; n < 2; ++n) _Pragma("unroll") for (int k = 0; k < 2; ++k) dst[n][k] = *(const LAS bf16x8*)(lds + PG8_SB(b, h) + boff + n * 2048 + k * 1024); } while (0)
; #define PG8_WAIT_V(n) asm volatile("s_waitcnt vmcnt(" #n ")" ::: "memory")
; #define PG8_WAIT_L(n) asm volatile("s_waitcnt lgkmcnt(" #n ")" ::: "memory")
; #define PG8_BAR __builtin_amdgcn_s_barrier()
; #define PG8_SCHED __builtin_amdgcn_sched_barrier(0)
; template <class Epi, bool ALIGN_EPI = true, bool SP2 = true>
; __device__ __forceinline__ void gemm_phase(LAS unsigned char* lds, const Gemm g, const Order& S, const Epi& E) {
;     ...
;         const char* nA = has_next ? (const char*)(nxt.z ? g.A1 : g.A0) + (size_t)nxt.pm * tstepA + (size_t)nxt.kt0 * kstep : cA; const char* nB = has_next ? (const char*)(nxt.z ? g.B1 : g.B0) + (size_t)nxt.pn * tstepB + (size_t)nxt.kt0 * kstep : cB;
;         const int nt = cur.nkt;
;         for (int t = 0; t < nt; t += 2) {
;             const bool last = (t == nt - 2);
;             const char* a1 = cA + (size_t)(t + 1) * kstep;
;             const char* a2 = last ? nA : cA + (size_t)(t + 2) * kstep; const char* b2 = last ? nB : cB + (size_t)(t + 2) * kstep;
;             const char* a3 = a2 + kstep; const char* b3 = b2 + kstep;
;             if constexpr (SP2) {
;             PG8_LDB(B0, 0, 0); PG8_LDB(B1, 0, 1); PG8_SCHED; PG8_LDA(At, 0, 0); PG8_STAGE(PG8_SA(1, 1), a1 + hstepA, voffA);
;             PG8_WAIT_V(8); PG8_WAIT_L(0); PG8_BAR; PG8_MMA(0, 0, At, B0); PG8_MMA(0, 1, At, B1); PG8_BAR; PG8_SCHED;
;     ...
;         for (int a = 0; a < 2; ++a)
; #pragma unroll
;             for (int b = 0; b < 2; ++b)
; #pragma unroll
;                 for (int m = 0; m < 4; ++m)
; #pragma unroll
;                     for (int n = 0; n < 2; ++n) acc[a][b][m][n] = (f32x4){0.f, 0.f, 0.f, 0.f};
;         }
;         cur = nxt; cA = nA; cB = nB; ++ui;
.LBB0_1096:
	s_add_i32 s13, s55, -2
	s_add_u32 s59, s62, 0x100
	v_mov_b32_e32 v2, 0
	s_addc_u32 s69, s63, 0
	s_mov_b32 s64, 0
	v_mov_b32_e32 v3, v2
	v_mov_b32_e32 v4, v2
	v_mov_b32_e32 v5, v2
	v_mov_b32_e32 v6, v2
	v_mov_b32_e32 v7, v2
	v_mov_b32_e32 v8, v2
	v_mov_b32_e32 v9, v2
	v_mov_b32_e32 v18, v2
	v_mov_b32_e32 v19, v2
	v_mov_b32_e32 v20, v2
	v_mov_b32_e32 v21, v2
	v_mov_b32_e32 v22, v2
	v_mov_b32_e32 v23, v2
	v_mov_b32_e32 v24, v2
	v_mov_b32_e32 v25, v2
	v_mov_b32_e32 v34, v2
	v_mov_b32_e32 v35, v2
	v_mov_b32_e32 v36, v2
	v_mov_b32_e32 v37, v2
	v_mov_b32_e32 v38, v2
	v_mov_b32_e32 v39, v2
	v_mov_b32_e32 v40, v2
	v_mov_b32_e32 v41, v2
	v_mov_b32_e32 v50, v2
	v_mov_b32_e32 v51, v2
	v_mov_b32_e32 v52, v2
	v_mov_b32_e32 v53, v2
	v_mov_b32_e32 v54, v2
	v_mov_b32_e32 v55, v2
	v_mov_b32_e32 v56, v2
	v_mov_b32_e32 v57, v2
	v_mov_b32_e32 v10, v2
	v_mov_b32_e32 v11, v2
	v_mov_b32_e32 v12, v2
	v_mov_b32_e32 v13, v2
	v_mov_b32_e32 v14, v2
	v_mov_b32_e32 v15, v2
	v_mov_b32_e32 v16, v2
	v_mov_b32_e32 v17, v2
	v_mov_b32_e32 v26, v2
	v_mov_b32_e32 v27, v2
	v_mov_b32_e32 v28, v2
	v_mov_b32_e32 v29, v2
	v_mov_b32_e32 v30, v2
	v_mov_b32_e32 v31, v2
	v_mov_b32_e32 v32, v2
	v_mov_b32_e32 v33, v2
	v_mov_b32_e32 v42, v2
	v_mov_b32_e32 v43, v2
	v_mov_b32_e32 v44, v2
	v_mov_b32_e32 v45, v2
	v_mov_b32_e32 v46, v2
	v_mov_b32_e32 v47, v2
	v_mov_b32_e32 v48, v2
	v_mov_b32_e32 v49, v2
	v_mov_b32_e32 v58, v2
	v_mov_b32_e32 v59, v2
	v_mov_b32_e32 v60, v2
	v_mov_b32_e32 v61, v2
	v_mov_b32_e32 v62, v2
	v_mov_b32_e32 v63, v2
	v_mov_b32_e32 v64, v2
	v_mov_b32_e32 v65, v2
	v_mov_b32_e32 v66, v2
	v_mov_b32_e32 v67, v2
	v_mov_b32_e32 v68, v2
	v_mov_b32_e32 v69, v2
	v_mov_b32_e32 v70, v2
	v_mov_b32_e32 v71, v2
	v_mov_b32_e32 v72, v2
	v_mov_b32_e32 v73, v2
	v_mov_b32_e32 v82, v2
	v_mov_b32_e32 v83, v2
	v_mov_b32_e32 v84, v2
	v_mov_b32_e32 v85, v2
	v_mov_b32_e32 v86, v2
	v_mov_b32_e32 v87, v2
	v_mov_b32_e32 v88, v2
	v_mov_b32_e32 v89, v2
	v_mov_b32_e32 v98, v2
	v_mov_b32_e32 v99, v2
	v_mov_b32_e32 v100, v2
	v_mov_b32_e32 v101, v2
	v_mov_b32_e32 v102, v2
	v_mov_b32_e32 v103, v2
	v_mov_b32_e32 v104, v2
	v_mov_b32_e32 v105, v2
	v_mov_b32_e32 v114, v2
	v_mov_b32_e32 v115, v2
	v_mov_b32_e32 v116, v2
	v_mov_b32_e32 v117, v2
	v_mov_b32_e32 v118, v2
	v_mov_b32_e32 v119, v2
	v_mov_b32_e32 v120, v2
	v_mov_b32_e32 v121, v2
	v_mov_b32_e32 v74, v2
	v_mov_b32_e32 v75, v2
	v_mov_b32_e32 v76, v2
	v_mov_b32_e32 v77, v2
	v_mov_b32_e32 v78, v2
	v_mov_b32_e32 v79, v2
	v_mov_b32_e32 v80, v2
	v_mov_b32_e32 v81, v2
	v_mov_b32_e32 v90, v2
	v_mov_b32_e32 v91, v2
	v_mov_b32_e32 v92, v2
	v_mov_b32_e32 v93, v2
	v_mov_b32_e32 v94, v2
	v_mov_b32_e32 v95, v2
	v_mov_b32_e32 v96, v2
	v_mov_b32_e32 v97, v2
	v_mov_b32_e32 v106, v2
	v_mov_b32_e32 v107, v2
	v_mov_b32_e32 v108, v2
	v_mov_b32_e32 v109, v2
	v_mov_b32_e32 v110, v2
	v_mov_b32_e32 v111, v2
	v_mov_b32_e32 v112, v2
	v_mov_b32_e32 v113, v2
	v_mov_b32_e32 v122, v2
	v_mov_b32_e32 v123, v2
	v_mov_b32_e32 v124, v2
	v_mov_b32_e32 v125, v2
	v_mov_b32_e32 v126, v2
	v_mov_b32_e32 v127, v2
	v_mov_b32_e32 v128, v2
	v_mov_b32_e32 v129, v2
	.p2align	6
.LBB0_1097:
	s_add_i32 s70, s64, 2
	s_add_u32 s62, s60, 0x100
	s_addc_u32 s63, s61, 0
	s_add_i32 s71, 0, 0x10000
	s_cmp_eq_u32 s13, s64
	s_cselect_b32 s67, s15, s63
	s_cselect_b32 s66, s14, s62
	v_add_u32_e32 v158, s71, v160
	s_cselect_b32 s65, s57, s69
	s_cselect_b32 s64, s56, s59
	s_add_i32 s72, 0, 0x14000
	ds_read_b128 v[162:165], v158
	ds_read_b128 v[166:169], v158 offset:1024
	ds_read_b128 v[170:173], v158 offset:2048
	ds_read_b128 v[174:177], v158 offset:3072
	v_add_u32_e32 v158, s72, v160
	ds_read_b128 v[178:181], v158
	ds_read_b128 v[182:185], v158 offset:1024
	ds_read_b128 v[186:189], v158 offset:2048
	ds_read_b128 v[190:193], v158 offset:3072
	v_lshl_add_u64 v[158:159], s[60:61], 0, v[154:155]
	s_add_i32 m0, s35, 0xc000
	ds_read_b128 v[194:197], v161
	ds_read_b128 v[198:201], v161 offset:1024
	ds_read_b128 v[224:227], v161 offset:2048
	ds_read_b128 v[228:231], v161 offset:3072
	ds_read_b128 v[232:235], v161 offset:4096
	ds_read_b128 v[236:239], v161 offset:5120
	ds_read_b128 v[240:243], v161 offset:6144
	ds_read_b128 v[244:247], v161 offset:7168
	global_load_lds_dwordx4 v[158:159], off
	v_lshl_add_u64 v[158:159], s[60:61], 0, v[156:157]
	s_add_i32 m0, s35, 0xe000
	s_nop 0
	global_load_lds_dwordx4 v[158:159], off
	s_waitcnt vmcnt(8)
	s_waitcnt lgkmcnt(0)
	s_barrier
	s_setprio 1
	s_waitcnt lgkmcnt(0)
	v_mfma_f32_16x16x32_bf16 v[126:129], v[162:165], v[194:197], v[126:129]
	v_mfma_f32_16x16x32_bf16 v[122:125], v[170:173], v[194:197], v[122:125]
	v_mfma_f32_16x16x32_bf16 v[110:113], v[162:165], v[224:227], v[110:113]
	v_mfma_f32_16x16x32_bf16 v[106:109], v[170:173], v[224:227], v[106:109]
	v_mfma_f32_16x16x32_bf16 v[94:97], v[162:165], v[232:235], v[94:97]
	v_mfma_f32_16x16x32_bf16 v[90:93], v[170:173], v[232:235], v[90:93]
	v_mfma_f32_16x16x32_bf16 v[78:81], v[162:165], v[240:243], v[78:81]
	v_mfma_f32_16x16x32_bf16 v[74:77], v[170:173], v[240:243], v[74:77]
	v_mfma_f32_16x16x32_bf16 v[126:129], v[166:169], v[198:201], v[126:129]
	v_mfma_f32_16x16x32_bf16 v[122:125], v[174:177], v[198:201], v[122:125]
	v_mfma_f32_16x16x32_bf16 v[110:113], v[166:169], v[228:231], v[110:113]
	v_mfma_f32_16x16x32_bf16 v[106:109], v[174:177], v[228:231], v[106:109]
	v_mfma_f32_16x16x32_bf16 v[94:97], v[166:169], v[236:239], v[94:97]
	v_mfma_f32_16x16x32_bf16 v[90:93], v[174:177], v[236:239], v[90:93]
	v_mfma_f32_16x16x32_bf16 v[78:81], v[166:169], v[244:247], v[78:81]
	v_mfma_f32_16x16x32_bf16 v[74:77], v[174:177], v[244:247], v[74:77]
	s_setprio 0
	s_setprio 1
	v_mfma_f32_16x16x32_bf16 v[118:121], v[178:181], v[194:197], v[118:121]
	v_mfma_f32_16x16x32_bf16 v[114:117], v[186:189], v[194:197], v[114:117]
	v_mfma_f32_16x16x32_bf16 v[102:105], v[178:181], v[224:227], v[102:105]
	v_mfma_f32_16x16x32_bf16 v[98:101], v[186:189], v[224:227], v[98:101]
	v_mfma_f32_16x16x32_bf16 v[86:89], v[178:181], v[232:235], v[86:89]
	v_mfma_f32_16x16x32_bf16 v[82:85], v[186:189], v[232:235], v[82:85]
	v_mfma_f32_16x16x32_bf16 v[70:73], v[178:181], v[240:243], v[70:73]
	v_mfma_f32_16x16x32_bf16 v[66:69], v[186:189], v[240:243], v[66:69]
	v_mfma_f32_16x16x32_bf16 v[118:121], v[182:185], v[198:201], v[118:121]
	v_mfma_f32_16x16x32_bf16 v[114:117], v[190:193], v[198:201], v[114:117]
	v_mfma_f32_16x16x32_bf16 v[102:105], v[182:185], v[228:231], v[102:105]
	v_mfma_f32_16x16x32_bf16 v[98:101], v[190:193], v[228:231], v[98:101]
	v_mfma_f32_16x16x32_bf16 v[86:89], v[182:185], v[236:239], v[86:89]
	v_mfma_f32_16x16x32_bf16 v[82:85], v[190:193], v[236:239], v[82:85]
	v_mfma_f32_16x16x32_bf16 v[70:73], v[182:185], v[244:247], v[70:73]
	v_mfma_f32_16x16x32_bf16 v[66:69], v[190:193], v[244:247], v[66:69]
	s_setprio 0
	s_barrier
; #define PG8_STAGE(bufoff, gbase, voff) do { _Pragma("unroll") for (int _i = 0; _i < 2; ++_i) \
;         __builtin_amdgcn_global_load_lds((const unsigned*)((const char*)(gbase) + (voff)[_i]), (LAS unsigned*)(lds + (bufoff) + ldsw + _i * 8192), 16, 0, 0); } while (0)
; #define PG8_LDA(dst, b, h) do { _Pragma("unroll") for (int m = 0; m < 4; ++m) _Pragma("unroll") for (int k = 0; k < 2; ++k) dst[m][k] = *(const LAS bf16x8*)(lds + PG8_SA(b, h) + aoff + m * 2048 + k * 1024); } while (0)
; #define PG8_LDB(dst, b, h) do { _Pragma("unroll") for (int n = 0; n < 2; ++n) _Pragma("unroll") for (int k = 0; k < 2; ++k) dst[n][k] = *(const LAS bf16x8*)(lds + PG8_SB(b, h) + boff + n * 2048 + k * 1024); } while (0)
; #define PG8_MMA(ai, bj, At, Bt) do { __builtin_amdgcn_s_setprio(1); _Pragma("unroll") for (int m = 0; m < 4; ++m) _Pragma("unroll") for (int n = 0; n < 2; ++n) _Pragma("unroll") for (int k = 0; k < 2; ++k) \
;         acc[ai][bj][m][n] = __builtin_amdgcn_mfma_f32_16x16x32_bf16(Bt[n][k], At[m][k], acc[ai][bj][m][n], 0, 0, 0); __builtin_amdgcn_s_setprio(0); } while (0)
; #define PG8_WAIT_V(n) asm volatile("s_waitcnt vmcnt(" #n ")" ::: "memory")
; #define PG8_WAIT_L(n) asm volatile("s_waitcnt lgkmcnt(" #n ")" ::: "memory")
; #define PG8_BAR __builtin_amdgcn_s_barrier()
; #define PG8_SCHED __builtin_amdgcn_sched_barrier(0)
; template <class Epi, bool ALIGN_EPI = true, bool SP2 = true>
; __device__ __forceinline__ void gemm_phase(LAS unsigned char* lds, const Gemm g, const Order& S, const Epi& E) {
;     ...
;             PG8_LDA(At, 0, 1); PG8_STAGE(PG8_SB(0, 0), b2, voffB); PG8_STAGE(PG8_SB(0, 1), b2 + hstepB, voffB); PG8_STAGE(PG8_SA(0, 0), a2, voffA);
;             PG8_WAIT_V(8); PG8_WAIT_L(0); PG8_BAR; PG8_MMA(1, 0, At, B0); PG8_MMA(1, 1, At, B1); PG8_BAR; PG8_SCHED;
;             PG8_LDB(B0, 1, 0); PG8_LDB(B1, 1, 1); PG8_SCHED; PG8_LDA(At, 1, 0); PG8_STAGE(PG8_SA(0, 1), a2 + hstepA, voffA);
;             PG8_WAIT_V(8); PG8_WAIT_L(0); PG8_BAR; PG8_MMA(0, 0, At, B0); PG8_MMA(0, 1, At, B1); PG8_BAR; PG8_SCHED;
	s_add_i32 s60, s71, s21
	v_lshl_add_u64 v[158:159], s[64:65], 0, v[0:1]
	s_mov_b32 m0, s60
	ds_read_b128 v[194:197], v161 offset:16384
	ds_read_b128 v[198:201], v161 offset:17408
	ds_read_b128 v[224:227], v161 offset:18432
	ds_read_b128 v[228:231], v161 offset:19456
	ds_read_b128 v[232:235], v161 offset:20480
	ds_read_b128 v[236:239], v161 offset:21504
	ds_read_b128 v[240:243], v161 offset:22528
	ds_read_b128 v[244:247], v161 offset:23552
	global_load_lds_dwordx4 v[158:159], off
	s_add_i32 m0, s60, 0x2000
	s_add_u32 s60, s64, 0xb0000
	v_lshl_add_u64 v[202:203], s[64:65], 0, v[134:135]
	s_addc_u32 s61, s65, 0
	s_add_i32 s71, s72, s21
	global_load_lds_dwordx4 v[202:203], off
	v_lshl_add_u64 v[210:211], s[60:61], 0, v[0:1]
	s_mov_b32 m0, s71
	v_lshl_add_u64 v[248:249], s[66:67], 0, v[132:133]
	global_load_lds_dwordx4 v[210:211], off
	v_lshl_add_u64 v[210:211], s[60:61], 0, v[134:135]
	s_add_i32 m0, s71, 0x2000
	s_nop 0
	global_load_lds_dwordx4 v[210:211], off
	v_lshl_add_u64 v[210:211], s[66:67], 0, v[130:131]
	s_mov_b32 m0, s35
	s_nop 0
	global_load_lds_dwordx4 v[210:211], off
	s_mov_b32 m0, s40
	s_nop 0
	global_load_lds_dwordx4 v[248:249], off
	s_waitcnt vmcnt(8)
	s_waitcnt lgkmcnt(0)
	s_barrier
	s_setprio 1
	s_waitcnt lgkmcnt(0)
	v_mfma_f32_16x16x32_bf16 v[62:65], v[162:165], v[194:197], v[62:65]
	v_mfma_f32_16x16x32_bf16 v[58:61], v[170:173], v[194:197], v[58:61]
	v_mfma_f32_16x16x32_bf16 v[46:49], v[162:165], v[224:227], v[46:49]
	v_mfma_f32_16x16x32_bf16 v[42:45], v[170:173], v[224:227], v[42:45]
	v_mfma_f32_16x16x32_bf16 v[30:33], v[162:165], v[232:235], v[30:33]
	v_mfma_f32_16x16x32_bf16 v[26:29], v[170:173], v[232:235], v[26:29]
	v_mfma_f32_16x16x32_bf16 v[14:17], v[162:165], v[240:243], v[14:17]
	v_mfma_f32_16x16x32_bf16 v[10:13], v[170:173], v[240:243], v[10:13]
	v_mfma_f32_16x16x32_bf16 v[62:65], v[166:169], v[198:201], v[62:65]
	v_mfma_f32_16x16x32_bf16 v[58:61], v[174:177], v[198:201], v[58:61]
	v_mfma_f32_16x16x32_bf16 v[46:49], v[166:169], v[228:231], v[46:49]
	v_mfma_f32_16x16x32_bf16 v[42:45], v[174:177], v[228:231], v[42:45]
	v_mfma_f32_16x16x32_bf16 v[30:33], v[166:169], v[236:239], v[30:33]
	v_mfma_f32_16x16x32_bf16 v[26:29], v[174:177], v[236:239], v[26:29]
	v_mfma_f32_16x16x32_bf16 v[14:17], v[166:169], v[244:247], v[14:17]
	v_mfma_f32_16x16x32_bf16 v[10:13], v[174:177], v[244:247], v[10:13]
	s_setprio 0
	s_setprio 1
	v_mfma_f32_16x16x32_bf16 v[54:57], v[178:181], v[194:197], v[54:57]
	v_mfma_f32_16x16x32_bf16 v[50:53], v[186:189], v[194:197], v[50:53]
	v_mfma_f32_16x16x32_bf16 v[38:41], v[178:181], v[224:227], v[38:41]
	v_mfma_f32_16x16x32_bf16 v[34:37], v[186:189], v[224:227], v[34:37]
	v_mfma_f32_16x16x32_bf16 v[22:25], v[178:181], v[232:235], v[22:25]
	v_mfma_f32_16x16x32_bf16 v[18:21], v[186:189], v[232:235], v[18:21]
	v_mfma_f32_16x16x32_bf16 v[6:9], v[178:181], v[240:243], v[6:9]
	v_mfma_f32_16x16x32_bf16 v[2:5], v[186:189], v[240:243], v[2:5]
	v_mfma_f32_16x16x32_bf16 v[54:57], v[182:185], v[198:201], v[54:57]
	v_mfma_f32_16x16x32_bf16 v[50:53], v[190:193], v[198:201], v[50:53]
	v_mfma_f32_16x16x32_bf16 v[38:41], v[182:185], v[228:231], v[38:41]
	v_mfma_f32_16x16x32_bf16 v[34:37], v[190:193], v[228:231], v[34:37]
	v_mfma_f32_16x16x32_bf16 v[22:25], v[182:185], v[236:239], v[22:25]
	v_mfma_f32_16x16x32_bf16 v[18:21], v[190:193], v[236:239], v[18:21]
	v_mfma_f32_16x16x32_bf16 v[6:9], v[182:185], v[244:247], v[6:9]
	v_mfma_f32_16x16x32_bf16 v[2:5], v[190:193], v[244:247], v[2:5]
	s_setprio 0
	s_barrier
	s_add_i32 s71, 0, 0x18000
	s_add_i32 s72, 0, 0x1c000
	v_add_u32_e32 v174, s71, v160
	v_add_u32_e32 v190, s72, v160
	ds_read_b128 v[162:165], v174
	ds_read_b128 v[166:169], v174 offset:1024
	ds_read_b128 v[170:173], v174 offset:2048
	ds_read_b128 v[174:177], v174 offset:3072
	ds_read_b128 v[178:181], v190
	ds_read_b128 v[182:185], v190 offset:1024
	ds_read_b128 v[186:189], v190 offset:2048
	ds_read_b128 v[190:193], v190 offset:3072
	s_add_u32 s60, s66, 0xb0000
	s_addc_u32 s61, s67, 0
	s_mov_b32 m0, s42
	v_lshl_add_u64 v[250:251], s[60:61], 0, v[130:131]
	ds_read_b128 v[194:197], v161 offset:32768
	ds_read_b128 v[198:201], v161 offset:33792
	ds_read_b128 v[224:227], v161 offset:34816
	ds_read_b128 v[228:231], v161 offset:35840
	ds_read_b128 v[232:235], v161 offset:36864
	ds_read_b128 v[236:239], v161 offset:37888
	ds_read_b128 v[240:243], v161 offset:38912
	ds_read_b128 v[244:247], v161 offset:39936
	global_load_lds_dwordx4 v[250:251], off
	v_lshl_add_u64 v[250:251], s[60:61], 0, v[132:133]
	s_mov_b32 m0, s44
	s_nop 0
	global_load_lds_dwordx4 v[250:251], off
	s_waitcnt vmcnt(8)
	s_waitcnt lgkmcnt(0)
	s_barrier
; #define PG8_STAGE(bufoff, gbase, voff) do { _Pragma("unroll") for (int _i = 0; _i < 2; ++_i) \
;         __builtin_amdgcn_global_load_lds((const unsigned*)((const char*)(gbase) + (voff)[_i]), (LAS unsigned*)(lds + (bufoff) + ldsw + _i * 8192), 16, 0, 0); } while (0)
; #define PG8_LDA(dst, b, h) do { _Pragma("unroll") for (int m = 0; m < 4; ++m) _Pragma("unroll") for (int k = 0; k < 2; ++k) dst[m][k] = *(const LAS bf16x8*)(lds + PG8_SA(b, h) + aoff + m * 2048 + k * 1024); } while (0)
; #define PG8_MMA(ai, bj, At, Bt) do { __builtin_amdgcn_s_setprio(1); _Pragma("unroll") for (int m = 0; m < 4; ++m) _Pragma("unroll") for (int n = 0; n < 2; ++n) _Pragma("unroll") for (int k = 0; k < 2; ++k) \
;         acc[ai][bj][m][n] = __builtin_amdgcn_mfma_f32_16x16x32_bf16(Bt[n][k], At[m][k], acc[ai][bj][m][n], 0, 0, 0); __builtin_amdgcn_s_setprio(0); } while (0)
; #define PG8_WAIT_V(n) asm volatile("s_waitcnt vmcnt(" #n ")" ::: "memory")
; #define PG8_WAIT_L(n) asm volatile("s_waitcnt lgkmcnt(" #n ")" ::: "memory")
; #define PG8_BAR __builtin_amdgcn_s_barrier()
; #define PG8_SCHED __builtin_amdgcn_sched_barrier(0)
; template <class Epi, bool ALIGN_EPI = true, bool SP2 = true>
; __device__ __forceinline__ void gemm_phase(LAS unsigned char* lds, const Gemm g, const Order& S, const Epi& E) {
;     ...
;         for (int t = 0; t < nt; t += 2) {
;     ...
;             PG8_WAIT_V(8); PG8_WAIT_L(0); PG8_BAR; PG8_MMA(0, 0, At, B0); PG8_MMA(0, 1, At, B1); PG8_BAR; PG8_SCHED;
;             PG8_LDA(At, 1, 1); PG8_STAGE(PG8_SB(1, 0), b3, voffB); PG8_STAGE(PG8_SB(1, 1), b3 + hstepB, voffB); PG8_STAGE(PG8_SA(1, 0), a3, voffA);
;             PG8_WAIT_V(8); PG8_WAIT_L(0); PG8_BAR; PG8_MMA(1, 0, At, B0); PG8_MMA(1, 1, At, B1); PG8_BAR; PG8_SCHED;
	s_setprio 1
	s_waitcnt lgkmcnt(0)
	v_mfma_f32_16x16x32_bf16 v[126:129], v[162:165], v[194:197], v[126:129]
	v_mfma_f32_16x16x32_bf16 v[122:125], v[170:173], v[194:197], v[122:125]
	v_mfma_f32_16x16x32_bf16 v[110:113], v[162:165], v[224:227], v[110:113]
	v_mfma_f32_16x16x32_bf16 v[106:109], v[170:173], v[224:227], v[106:109]
	v_mfma_f32_16x16x32_bf16 v[94:97], v[162:165], v[232:235], v[94:97]
	v_mfma_f32_16x16x32_bf16 v[90:93], v[170:173], v[232:235], v[90:93]
	v_mfma_f32_16x16x32_bf16 v[78:81], v[162:165], v[240:243], v[78:81]
	v_mfma_f32_16x16x32_bf16 v[74:77], v[170:173], v[240:243], v[74:77]
	v_mfma_f32_16x16x32_bf16 v[126:129], v[166:169], v[198:201], v[126:129]
	v_mfma_f32_16x16x32_bf16 v[122:125], v[174:177], v[198:201], v[122:125]
	v_mfma_f32_16x16x32_bf16 v[110:113], v[166:169], v[228:231], v[110:113]
	v_mfma_f32_16x16x32_bf16 v[106:109], v[174:177], v[228:231], v[106:109]
	v_mfma_f32_16x16x32_bf16 v[94:97], v[166:169], v[236:239], v[94:97]
	v_mfma_f32_16x16x32_bf16 v[90:93], v[174:177], v[236:239], v[90:93]
	v_mfma_f32_16x16x32_bf16 v[78:81], v[166:169], v[244:247], v[78:81]
	v_mfma_f32_16x16x32_bf16 v[74:77], v[174:177], v[244:247], v[74:77]
	s_setprio 0
	s_setprio 1
	v_mfma_f32_16x16x32_bf16 v[118:121], v[178:181], v[194:197], v[118:121]
	v_mfma_f32_16x16x32_bf16 v[114:117], v[186:189], v[194:197], v[114:117]
	v_mfma_f32_16x16x32_bf16 v[102:105], v[178:181], v[224:227], v[102:105]
	v_mfma_f32_16x16x32_bf16 v[98:101], v[186:189], v[224:227], v[98:101]
	v_mfma_f32_16x16x32_bf16 v[86:89], v[178:181], v[232:235], v[86:89]
	v_mfma_f32_16x16x32_bf16 v[82:85], v[186:189], v[232:235], v[82:85]
	v_mfma_f32_16x16x32_bf16 v[70:73], v[178:181], v[240:243], v[70:73]
	v_mfma_f32_16x16x32_bf16 v[66:69], v[186:189], v[240:243], v[66:69]
	v_mfma_f32_16x16x32_bf16 v[118:121], v[182:185], v[198:201], v[118:121]
	v_mfma_f32_16x16x32_bf16 v[114:117], v[190:193], v[198:201], v[114:117]
	v_mfma_f32_16x16x32_bf16 v[102:105], v[182:185], v[228:231], v[102:105]
	v_mfma_f32_16x16x32_bf16 v[98:101], v[190:193], v[228:231], v[98:101]
	v_mfma_f32_16x16x32_bf16 v[86:89], v[182:185], v[236:239], v[86:89]
	v_mfma_f32_16x16x32_bf16 v[82:85], v[190:193], v[236:239], v[82:85]
	v_mfma_f32_16x16x32_bf16 v[70:73], v[182:185], v[244:247], v[70:73]
	v_mfma_f32_16x16x32_bf16 v[66:69], v[190:193], v[244:247], v[66:69]
	s_setprio 0
	s_barrier
	s_add_i32 s60, s71, s21
	v_lshl_add_u64 v[158:159], v[158:159], 0, s[26:27]
	s_mov_b32 m0, s60
	ds_read_b128 v[194:197], v161 offset:49152
	ds_read_b128 v[198:201], v161 offset:50176
	ds_read_b128 v[224:227], v161 offset:51200
	ds_read_b128 v[228:231], v161 offset:52224
	ds_read_b128 v[232:235], v161 offset:53248
	ds_read_b128 v[236:239], v161 offset:54272
	ds_read_b128 v[240:243], v161 offset:55296
	ds_read_b128 v[244:247], v161 offset:56320
	global_load_lds_dwordx4 v[158:159], off
	s_add_i32 m0, s60, 0x2000
	s_add_u32 s60, s64, 0xb0080
	v_lshl_add_u64 v[158:159], v[202:203], 0, s[26:27]
	s_addc_u32 s61, s65, 0
	s_add_i32 s64, s72, s21
	global_load_lds_dwordx4 v[158:159], off
	v_lshl_add_u64 v[158:159], s[60:61], 0, v[0:1]
	s_mov_b32 m0, s64
	s_nop 0
	global_load_lds_dwordx4 v[158:159], off
	v_lshl_add_u64 v[158:159], s[60:61], 0, v[134:135]
	s_add_i32 m0, s64, 0x2000
	s_nop 0
	global_load_lds_dwordx4 v[158:159], off
	v_lshl_add_u64 v[158:159], v[210:211], 0, s[26:27]
	s_mov_b32 m0, s48
	s_nop 0
	global_load_lds_dwordx4 v[158:159], off
	v_lshl_add_u64 v[158:159], v[248:249], 0, s[26:27]
	s_mov_b32 m0, s49
	s_nop 0
	global_load_lds_dwordx4 v[158:159], off
	s_waitcnt vmcnt(8)
	s_waitcnt lgkmcnt(0)
	s_barrier
	s_setprio 1
	s_waitcnt lgkmcnt(0)
	v_mfma_f32_16x16x32_bf16 v[62:65], v[162:165], v[194:197], v[62:65]
	v_mfma_f32_16x16x32_bf16 v[58:61], v[170:173], v[194:197], v[58:61]
	v_mfma_f32_16x16x32_bf16 v[46:49], v[162:165], v[224:227], v[46:49]
	v_mfma_f32_16x16x32_bf16 v[42:45], v[170:173], v[224:227], v[42:45]
	v_mfma_f32_16x16x32_bf16 v[30:33], v[162:165], v[232:235], v[30:33]
	v_mfma_f32_16x16x32_bf16 v[26:29], v[170:173], v[232:235], v[26:29]
	v_mfma_f32_16x16x32_bf16 v[14:17], v[162:165], v[240:243], v[14:17]
	v_mfma_f32_16x16x32_bf16 v[10:13], v[170:173], v[240:243], v[10:13]
	v_mfma_f32_16x16x32_bf16 v[62:65], v[166:169], v[198:201], v[62:65]
	v_mfma_f32_16x16x32_bf16 v[58:61], v[174:177], v[198:201], v[58:61]
	v_mfma_f32_16x16x32_bf16 v[46:49], v[166:169], v[228:231], v[46:49]
	v_mfma_f32_16x16x32_bf16 v[42:45], v[174:177], v[228:231], v[42:45]
	v_mfma_f32_16x16x32_bf16 v[30:33], v[166:169], v[236:239], v[30:33]
	v_mfma_f32_16x16x32_bf16 v[26:29], v[174:177], v[236:239], v[26:29]
	v_mfma_f32_16x16x32_bf16 v[14:17], v[166:169], v[244:247], v[14:17]
	v_mfma_f32_16x16x32_bf16 v[10:13], v[174:177], v[244:247], v[10:13]
	s_setprio 0
	s_setprio 1
	v_mfma_f32_16x16x32_bf16 v[54:57], v[178:181], v[194:197], v[54:57]
	v_mfma_f32_16x16x32_bf16 v[50:53], v[186:189], v[194:197], v[50:53]
	v_mfma_f32_16x16x32_bf16 v[38:41], v[178:181], v[224:227], v[38:41]
	v_mfma_f32_16x16x32_bf16 v[34:37], v[186:189], v[224:227], v[34:37]
	v_mfma_f32_16x16x32_bf16 v[22:25], v[178:181], v[232:235], v[22:25]
	v_mfma_f32_16x16x32_bf16 v[18:21], v[186:189], v[232:235], v[18:21]
	v_mfma_f32_16x16x32_bf16 v[6:9], v[178:181], v[240:243], v[6:9]
	v_mfma_f32_16x16x32_bf16 v[2:5], v[186:189], v[240:243], v[2:5]
	v_mfma_f32_16x16x32_bf16 v[54:57], v[182:185], v[198:201], v[54:57]
	v_mfma_f32_16x16x32_bf16 v[50:53], v[190:193], v[198:201], v[50:53]
	v_mfma_f32_16x16x32_bf16 v[38:41], v[182:185], v[228:231], v[38:41]
	v_mfma_f32_16x16x32_bf16 v[34:37], v[190:193], v[228:231], v[34:37]
	v_mfma_f32_16x16x32_bf16 v[22:25], v[182:185], v[236:239], v[22:25]
	v_mfma_f32_16x16x32_bf16 v[18:21], v[190:193], v[236:239], v[18:21]
	v_mfma_f32_16x16x32_bf16 v[6:9], v[182:185], v[244:247], v[6:9]
	v_mfma_f32_16x16x32_bf16 v[2:5], v[190:193], v[244:247], v[2:5]
	s_setprio 0
	s_barrier
	s_add_u32 s59, s59, 0x100
	s_addc_u32 s69, s69, 0
	s_cmp_ge_i32 s70, s55
	s_mov_b64 s[60:61], s[62:63]
	s_mov_b32 s64, s70
	s_cbranch_scc0 .LBB0_1097
	s_and_b64 vcc, exec, s[10:11]
	s_cbranch_vccz .LBB0_1105
